# LDS-read hoisting with register renaming in hg_unit state loop and attention QK block (waits adjusted, not removed); P2 work queue serves the long attention units first
# baseline (speedup 1.0000x reference)
; __global__ void __launch_bounds__(512, 2) fwd_megakernel(Ptrs Parg) {
;     ...
;           int it = (int)__builtin_amdgcn_readfirstlane(misc[2]);
;           while (it < 28 * NCH) { const int t2 = pg8::wg_tid(glds);
;               if (t2 == 0) nxt = atomicAdd(qctr, 1u);
;               if (it < 16 * NCH) { const int ch = it % NCH, bh = it / NCH; hg_unit(P, l, bh >> 3, bh & 7, ch, lds, t2); }
;               else if (it < 24 * NCH) { const int i2 = it - 16 * NCH; const int ch = i2 % NCH, bg = i2 / NCH; ssd_passA(P, l, bg >> 2, ch, bg & 3, lds, t2); }
;               else { const int i2 = it - 24 * NCH; const int n = i2 % NCH, bg = i2 / NCH; attn_unit(P, l, bg >> 1, bg & 1, n, lds, t2, true); }
.LBB0_299:
	s_movk_i32 s100, 0xc18
	s_movk_i32 s101, 0xfdfc
	s_cmp_lt_u32 s74, 0x204
	s_cselect_b32 s100, s100, s101
	s_add_i32 s74, s74, s100
	s_getreg_b32 s3, hwreg(HW_REG_HW_ID, 0, 6)
	s_and_b32 s3, s3, 63
	s_lshl_b32 s3, s3, 2
	s_add_i32 s3, s3, 0
	s_add_i32 s3, s3, 0x27ef0
	v_mov_b32_e32 v10, s3
	ds_read_b32 v10, v10
	s_waitcnt lgkmcnt(0)
	v_readfirstlane_b32 s3, v10
	s_nop 1
	v_lshl_add_u32 v98, s3, 6, v213
	s_nop 0
	v_cmp_eq_u32_e64 s[36:37], 0, v98
	s_and_saveexec_b64 s[4:5], s[36:37]
	s_cbranch_execz .LBB0_303
	s_mov_b64 s[8:9], exec
	v_mbcnt_lo_u32_b32 v10, s8, 0
	v_mbcnt_hi_u32_b32 v10, s9, v10
	v_cmp_eq_u32_e32 vcc, 0, v10
	s_and_saveexec_b64 s[6:7], vcc
	s_cbranch_execz .LBB0_302
	s_bcnt1_i32_b64 s3, s[8:9]
	v_mov_b32_e32 v11, s3
	global_atomic_add v11, v[0:1], v11, off sc0

; __device__ __forceinline__ void attn_unit(const Ptrs& P, int l, int b, int gk, int n, unsigned char* lds, int tid, bool dost) {
;     ...
;     const int head = gk * 8 + w;
;     hb[w * 128 + lane] = rb[bkt[lane] * 16 + head]; hb[w * 128 + 64 + lane] = rb[bkt[64 + lane] * 16 + head];
;     __syncthreads();
;     const float sink = P.att_sinks[l * 16 + head];
.LBB0_315:
	s_or_b64 exec, exec, s[4:5]
	v_lshlrev_b32_e32 v12, 2, v108
	v_add_u32_e32 v10, 0, v12
	v_add_u32_e32 v10, 0x27000, v10
	ds_read2st64_b32 v[150:151], v10 offset1:1
	v_lshl_add_u32 v11, s9, 3, v107
	s_add_i32 s9, 0, 0x27200
	v_lshlrev_b32_e32 v13, 2, v11
	v_readlane_b32 s4, v255, 24
	s_waitcnt lgkmcnt(0)
	v_lshlrev_b32_e32 v10, 6, v150
	v_add3_u32 v10, s9, v10, v13
	ds_read_b32 v152, v10
	v_lshl_add_u32 v10, v107, 9, s4
	v_add_u32_e32 v18, v10, v12
	s_cmp_eq_u32 s3, 0
	s_cselect_b64 s[4:5], -1, 0
	s_waitcnt lgkmcnt(0)
	ds_write_b32 v18, v152
	v_lshlrev_b32_e32 v17, 6, v151
	v_add3_u32 v13, s9, v17, v13
	ds_read_b32 v153, v13
	s_cmp_lg_u32 s3, 0
	s_mov_b64 s[6:7], -1
	s_waitcnt lgkmcnt(0)
	ds_write_b32 v18, v153 offset:256
	v_add_u32_e32 v18, s14, v11
	v_ashrrev_i32_e32 v19, 31, v18
	v_lshl_add_u64 v[18:19], v[18:19], 2, v[8:9]
	s_waitcnt lgkmcnt(0)
	s_barrier
	global_load_dword v17, v[18:19], off
	s_cbranch_scc0 .LBB0_317
	s_lshl_b32 s10, s8, 14
	s_add_i32 s20, s10, 0xffffff80
	s_lshl_b32 s17, s8, 4
	s_mov_b64 s[6:7], 0

; __device__ __forceinline__ float shx(float v, int o, int lane) { return __builtin_bit_cast(float, __builtin_amdgcn_ds_bpermute((lane ^ o) << 2, __builtin_bit_cast(int, v))); }
; __device__ __forceinline__ void attn_unit(const Ptrs& P, int l, int b, int gk, int n, unsigned char* lds, int tid, bool dost) {
;     ...
;         float mx = sink;
; #pragma unroll
;         for (int kt = 0; kt < 9; ++kt)
; #pragma unroll
;             for (int r = 0; r < 4; ++r) { const int dist = 128 + lc - 16 * kt - 4 * g - r; const int j = 16 * (qs + kt) + 4 * g + r;
;                 const bool valid = (dist >= 0) && (dist < 128) && (n >= 1) && (n >= 2 || j >= 128);
;                 const float lg = valid ? (st[kt][r] * 0.125f + hb[w * 128 + (dist & 127)]) : NEGV; st[kt][r] = lg; mx = fmaxf(mx, lg); }
; #pragma unroll
;         for (int r = 0; r < 4; ++r) { const int dist = tq - (4 * g + r); const bool valid = dist >= 0; const int bk = (dist >= 0 && dist < 128) ? bkt[dist & 127] : 31;
;             const float lg = valid ? (st[9][r] * 0.125f + rb[bk * 16 + head]) : NEGV; st[9][r] = lg; mx = fmaxf(mx, lg); }
;         mx = fmaxf(mx, shx(mx, 16, lane)); mx = fmaxf(mx, shx(mx, 32, lane));
;         float sum = 0.f;
; #pragma unroll
;         for (int kt = 0; kt < 10; ++kt)
; #pragma unroll
;             for (int r = 0; r < 4; ++r) { const float p = __expf(st[kt][r] - mx); st[kt][r] = p; sum += p; }
;         sum += shx(sum, 16, lane); sum += shx(sum, 32, lane);
;         const float inv = 1.0f / (sum + __expf(sink - mx));
.LBB0_320:
	s_or_b64 exec, exec, s[12:13]
	v_max3_f32 v41, v17, v73, v70
	v_max3_f32 v41, v41, v78, v72
	v_max3_f32 v41, v41, v79, v22
	v_max3_f32 v41, v41, v27, v23
	v_max3_f32 v41, v41, v71, v26
	v_max3_f32 v41, v41, v67, v66
	v_max3_f32 v41, v41, v69, v68
	v_max3_f32 v41, v41, v63, v62
	v_max3_f32 v41, v41, v65, v64
	v_max3_f32 v41, v41, v59, v58
	v_max3_f32 v41, v41, v61, v60
	v_max3_f32 v41, v41, v55, v54
	v_max3_f32 v41, v41, v57, v56
	v_max3_f32 v41, v41, v51, v50
	v_max3_f32 v41, v41, v53, v52
	v_max3_f32 v41, v41, v74, v47
	v_max3_f32 v41, v41, v49, v48
	v_max3_f32 v41, v41, v43, v42
	s_cmpk_lt_u32 s17, 0x80
	v_max3_f32 v41, v41, v44, v38
	s_cselect_b64 vcc, -1, 0
	v_cndmask_b32_e32 v45, v121, v124, vcc
	v_max3_f32 v41, v41, v39, v40
	v_add_u32_e32 v46, s15, v45
	ds_bpermute_b32 v45, v109, v41
	v_add_u32_e32 v147, 0, v119
	v_add_u32_e32 v130, 0x100, v147
	v_add_u32_e32 v148, 0x2000, v147
	s_add_i32 s12, s19, 1
	s_waitcnt lgkmcnt(0)
	v_max_f32_e32 v45, v45, v45
	v_max_f32_e32 v41, v41, v45
	ds_bpermute_b32 v45, v110, v41
	ds_read2_b64 v[150:153], v148 offset0:100 offset1:104
	s_add_i32 s15, s15, 16
	v_add_u32_e32 v118, 0x900, v118
	v_add_u32_e32 v119, 32, v119
	v_add_u32_e32 v122, 64, v122
	s_waitcnt lgkmcnt(1)
	v_max_f32_e32 v45, v45, v45
	v_max_f32_e32 v41, v41, v45
	v_sub_f32_e32 v23, v23, v41
	v_mul_f32_e32 v23, 0x3fb8aa3b, v23
	v_sub_f32_e32 v75, v78, v41
	v_exp_f32_e32 v78, v23
	v_sub_f32_e32 v23, v71, v41
	v_mul_f32_e32 v23, 0x3fb8aa3b, v23
	v_exp_f32_e32 v80, v23
	v_sub_f32_e32 v23, v26, v41
	v_mul_f32_e32 v23, 0x3fb8aa3b, v23
	v_exp_f32_e32 v81, v23
	v_sub_f32_e32 v23, v67, v41
	v_mul_f32_e32 v23, 0x3fb8aa3b, v23
	v_exp_f32_e32 v125, v23
	v_sub_f32_e32 v23, v66, v41
	v_mul_f32_e32 v23, 0x3fb8aa3b, v23
	v_exp_f32_e32 v138, v23
	v_sub_f32_e32 v23, v69, v41
	v_mul_f32_e32 v23, 0x3fb8aa3b, v23
	v_exp_f32_e32 v139, v23
	v_sub_f32_e32 v23, v68, v41
	v_mul_f32_e32 v23, 0x3fb8aa3b, v23
	v_sub_f32_e32 v45, v73, v41
	v_exp_f32_e32 v140, v23
	v_sub_f32_e32 v23, v63, v41
	v_mul_f32_e32 v45, 0x3fb8aa3b, v45
	v_sub_f32_e32 v70, v70, v41
	v_mul_f32_e32 v23, 0x3fb8aa3b, v23
	v_exp_f32_e32 v45, v45
	v_mul_f32_e32 v70, 0x3fb8aa3b, v70
	v_exp_f32_e32 v141, v23
	v_sub_f32_e32 v23, v62, v41
	v_exp_f32_e32 v70, v70
	v_mul_f32_e32 v75, 0x3fb8aa3b, v75
	v_sub_f32_e32 v72, v72, v41
	v_mul_f32_e32 v23, 0x3fb8aa3b, v23
	v_exp_f32_e32 v75, v75
	v_mul_f32_e32 v72, 0x3fb8aa3b, v72
	v_sub_f32_e32 v76, v79, v41
	v_exp_f32_e32 v142, v23
	v_sub_f32_e32 v23, v65, v41
	v_exp_f32_e32 v72, v72
	v_mul_f32_e32 v76, 0x3fb8aa3b, v76
	v_sub_f32_e32 v22, v22, v41
	v_mul_f32_e32 v23, 0x3fb8aa3b, v23
	v_add_f32_e32 v73, 0, v45
	v_exp_f32_e32 v76, v76
	v_mul_f32_e32 v22, 0x3fb8aa3b, v22
	v_exp_f32_e32 v62, v23
	v_sub_f32_e32 v23, v64, v41
	v_add_f32_e32 v73, v70, v73
	v_exp_f32_e32 v77, v22
	v_mul_f32_e32 v23, 0x3fb8aa3b, v23
	v_add_f32_e32 v73, v75, v73
	v_exp_f32_e32 v63, v23
	v_sub_f32_e32 v23, v59, v41
	v_add_f32_e32 v73, v72, v73
	v_sub_f32_e32 v27, v27, v41
	v_mul_f32_e32 v23, 0x3fb8aa3b, v23
	v_add_f32_e32 v73, v76, v73
	v_mul_f32_e32 v27, 0x3fb8aa3b, v27
	v_exp_f32_e32 v59, v23
	v_sub_f32_e32 v23, v58, v41
	v_add_f32_e32 v22, v77, v73
	v_exp_f32_e32 v73, v27
	v_mul_f32_e32 v23, 0x3fb8aa3b, v23
	v_exp_f32_e32 v143, v23
	v_sub_f32_e32 v23, v61, v41
	v_mul_f32_e32 v23, 0x3fb8aa3b, v23
	v_exp_f32_e32 v61, v23
	v_sub_f32_e32 v23, v60, v41
	v_add_f32_e32 v22, v73, v22
	v_mul_f32_e32 v23, 0x3fb8aa3b, v23
	v_add_f32_e32 v22, v78, v22
	v_exp_f32_e32 v144, v23
	v_sub_f32_e32 v23, v55, v41
	v_add_f32_e32 v22, v80, v22
	v_mul_f32_e32 v23, 0x3fb8aa3b, v23
	v_add_f32_e32 v22, v81, v22
	v_exp_f32_e32 v145, v23
	v_sub_f32_e32 v23, v54, v41
	v_add_f32_e32 v22, v125, v22
	v_mul_f32_e32 v23, 0x3fb8aa3b, v23
	v_add_f32_e32 v22, v138, v22
	v_exp_f32_e32 v146, v23
	v_sub_f32_e32 v23, v57, v41
	v_add_f32_e32 v22, v139, v22
	v_mul_f32_e32 v23, 0x3fb8aa3b, v23
	v_add_f32_e32 v22, v140, v22
	v_exp_f32_e32 v54, v23
	v_sub_f32_e32 v23, v56, v41
	v_add_f32_e32 v22, v141, v22
	v_mul_f32_e32 v23, 0x3fb8aa3b, v23
	v_add_f32_e32 v22, v142, v22
	v_exp_f32_e32 v55, v23
	v_sub_f32_e32 v23, v51, v41
	v_add_f32_e32 v22, v62, v22
	v_mul_f32_e32 v23, 0x3fb8aa3b, v23
	v_add_f32_e32 v22, v63, v22
	v_exp_f32_e32 v56, v23
	v_sub_f32_e32 v23, v50, v41
	v_add_f32_e32 v22, v59, v22
	v_mul_f32_e32 v23, 0x3fb8aa3b, v23
	v_add_f32_e32 v22, v143, v22
	v_exp_f32_e32 v57, v23
	v_sub_f32_e32 v23, v53, v41
	v_add_f32_e32 v22, v61, v22
	v_mul_f32_e32 v23, 0x3fb8aa3b, v23
	v_add_f32_e32 v22, v144, v22
	v_exp_f32_e32 v53, v23
	v_sub_f32_e32 v23, v52, v41
	v_add_f32_e32 v22, v145, v22
	v_mul_f32_e32 v23, 0x3fb8aa3b, v23
	v_add_f32_e32 v22, v146, v22
	v_exp_f32_e32 v52, v23
	v_sub_f32_e32 v23, v74, v41
	v_add_f32_e32 v22, v54, v22
	v_mul_f32_e32 v23, 0x3fb8aa3b, v23
	v_add_f32_e32 v22, v55, v22
	v_exp_f32_e32 v58, v23
	v_sub_f32_e32 v23, v47, v41
	v_add_f32_e32 v22, v56, v22
	v_mul_f32_e32 v23, 0x3fb8aa3b, v23
	v_add_f32_e32 v22, v57, v22
	v_exp_f32_e32 v60, v23
	v_add_f32_e32 v22, v53, v22
	v_add_f32_e32 v22, v52, v22
	v_add_f32_e32 v22, v58, v22
	v_add_f32_e32 v23, v60, v22
	v_sub_f32_e32 v22, v49, v41
	v_mul_f32_e32 v22, 0x3fb8aa3b, v22
	v_exp_f32_e32 v22, v22
	v_sub_f32_e32 v38, v38, v41
	v_sub_f32_e32 v39, v39, v41
	v_mul_f32_e32 v38, 0x3fb8aa3b, v38
	v_add_f32_e32 v26, v22, v23
	v_sub_f32_e32 v23, v48, v41
	v_mul_f32_e32 v23, 0x3fb8aa3b, v23
	v_exp_f32_e32 v23, v23
	v_mul_f32_e32 v39, 0x3fb8aa3b, v39
	v_exp_f32_e32 v49, v38
	v_exp_f32_e32 v50, v39
	v_add_f32_e32 v27, v23, v26
	v_sub_f32_e32 v26, v43, v41
	v_mul_f32_e32 v26, 0x3fb8aa3b, v26
	v_exp_f32_e32 v26, v26
	v_sub_f32_e32 v39, v40, v41
	v_mul_f32_e32 v39, 0x3fb8aa3b, v39
	v_exp_f32_e32 v51, v39
	v_add_f32_e32 v43, v26, v27
	v_sub_f32_e32 v27, v42, v41
	v_mul_f32_e32 v27, 0x3fb8aa3b, v27
	v_exp_f32_e32 v27, v27
	v_cvt_pk_bf16_f32 v64, v45, v70
	v_cvt_pk_bf16_f32 v65, v75, v72
	v_cvt_pk_bf16_f32 v67, v73, v78
	v_add_f32_e32 v42, v27, v43
	v_sub_f32_e32 v43, v44, v41
	v_mul_f32_e32 v43, 0x3fb8aa3b, v43
	v_exp_f32_e32 v48, v43
	s_nop 0
	v_cvt_pk_bf16_f32 v66, v76, v77
	v_cvt_pk_bf16_f32 v54, v54, v55
	v_add_f32_e32 v42, v48, v42
	v_add_f32_e32 v38, v49, v42
	v_add_f32_e32 v38, v50, v38
	v_add_f32_e32 v38, v51, v38
	ds_bpermute_b32 v39, v109, v38
	ds_read2st64_b64 v[42:45], v130 offset1:17
	v_cvt_pk_bf16_f32 v55, v56, v57
	v_cvt_pk_bf16_f32 v57, v58, v60
	v_cvt_pk_bf16_f32 v56, v53, v52
	s_waitcnt lgkmcnt(1)
; __device__ __forceinline__ unsigned pk2(float lo, float hi) { f32x2_t v = {lo, hi}; bf16x2_t b = __builtin_convertvector(v, bf16x2_t); return __builtin_bit_cast(unsigned, b); }
; __device__ __forceinline__ float shx(float v, int o, int lane) { return __builtin_bit_cast(float, __builtin_amdgcn_ds_bpermute((lane ^ o) << 2, __builtin_bit_cast(int, v))); }
; __device__ __forceinline__ f32x4 mfma32(bf16x8 a, bf16x8 b, f32x4 c) { return __builtin_amdgcn_mfma_f32_16x16x32_bf16(a, b, c, 0, 0, 0); }
; __device__ __forceinline__ bf16x8 pack8(f32x4 a, f32x4 b) { u32x4 w; w.x = pk2(a[0], a[1]); w.y = pk2(a[2], a[3]); w.z = pk2(b[0], b[1]); w.w = pk2(b[2], b[3]); return __builtin_bit_cast(bf16x8, w); }
; __device__ __forceinline__ void attn_unit(const Ptrs& P, int l, int b, int gk, int n, unsigned char* lds, int tid, bool dost) {
;     ...
;         sum += shx(sum, 16, lane); sum += shx(sum, 32, lane);
;         const float inv = 1.0f / (sum + __expf(sink - mx));
;         f32x4 o[4];
; #pragma unroll
;         for (int dt = 0; dt < 4; ++dt) o[dt] = (f32x4){0.f, 0.f, 0.f, 0.f};
; #pragma unroll
;         for (int j = 0; j < 5; ++j) {
;             const bf16x8 pb = pack8(st[2 * j], st[2 * j + 1]);
;             const int colA = 16 * (qs + 2 * j) + 4 * g; const int colB = (j < 4) ? (16 * (qs + 2 * j + 1) + 4 * g) : (256 + 4 * g);
; #pragma unroll
;             for (int dt = 0; dt < 4; ++dt) { const int d = 16 * dt + lc;
;                 const u32x2 lo = *(const u32x2*)(Vt + d * 280 + colA), hi = *(const u32x2*)(Vt + d * 280 + colB);
;                 o[dt] = mfma32(cat8(lo, hi), pb, o[dt]); }
;         }
; #pragma unroll
;         for (int dt = 0; dt < 4; ++dt) { u32x2 wv; wv.x = pk2(o[dt][0] * inv, o[dt][1] * inv); wv.y = pk2(o[dt][2] * inv, o[dt][3] * inv); if (dost) *(u32x2*)(qp + 16 * dt + 4 * g) = wv; }
	v_add_f32_e32 v38, v38, v39
	ds_bpermute_b32 v39, v110, v38
	ds_read2_b64 v[154:157], v147 offset1:4
	s_cmp_lt_u32 s19, 7
	s_mov_b32 s19, s12
	s_waitcnt lgkmcnt(1)
	v_add_f32_e32 v38, v38, v39
	v_sub_f32_e32 v39, v17, v41
	v_mul_f32_e32 v39, 0x3fb8aa3b, v39
	v_exp_f32_e32 v39, v39
	s_nop 0
	v_add_f32_e32 v47, v39, v38
	s_nop 0
	s_waitcnt lgkmcnt(0)
	v_mfma_f32_16x16x32_bf16 v[68:71], v[154:157], v[64:67], 0
	v_mov_b32_e32 v38, v44
	v_mov_b32_e32 v39, v45
	v_mov_b32_e32 v40, v150
	v_mov_b32_e32 v41, v151
	v_add_u32_e32 v44, 0x4000, v147
	ds_read2_b64 v[158:161], v44 offset0:192 offset1:196
	v_add_u32_e32 v45, 0x6800, v147
	v_mfma_f32_16x16x32_bf16 v[76:79], v[38:41], v[64:67], 0
	s_nop 0
	v_mov_b32_e32 v72, v152
	v_mov_b32_e32 v73, v153
	s_waitcnt lgkmcnt(0)
	v_mfma_f32_16x16x32_bf16 v[126:129], v[158:161], v[64:67], 0
	ds_read2st64_b64 v[38:41], v130 offset0:35 offset1:52
	ds_read2_b64 v[162:165], v45 offset0:36 offset1:40
	ds_read2_b64 v[166:169], v147 offset0:8 offset1:12
	ds_read2_b64 v[170:173], v148 offset0:108 offset1:112
	ds_read2_b64 v[174:177], v44 offset0:200 offset1:204
	ds_read2_b64 v[178:181], v45 offset0:44 offset1:48
	ds_read2_b64 v[182:185], v147 offset0:16 offset1:20
	ds_read2_b64 v[186:189], v147 offset0:24 offset1:28
	ds_read2_b64 v[190:193], v148 offset0:116 offset1:120
	ds_read2_b64 v[196:199], v44 offset0:208 offset1:212
	ds_read2_b64 v[200:203], v45 offset0:52 offset1:56
	s_waitcnt lgkmcnt(10)
	v_mov_b32_e32 v134, v40
	v_mov_b32_e32 v135, v41
	s_waitcnt lgkmcnt(9)
	v_mov_b32_e32 v136, v162
	v_mov_b32_e32 v137, v163
	v_mov_b32_e32 v130, v164
	v_mov_b32_e32 v131, v165
	v_mfma_f32_16x16x32_bf16 v[64:67], v[134:137], v[64:67], 0
	v_cvt_pk_bf16_f32 v135, v125, v138
	v_cvt_pk_bf16_f32 v136, v139, v140
	v_cvt_pk_bf16_f32 v137, v141, v142
	s_nop 0
	v_cvt_pk_bf16_f32 v134, v80, v81
	v_mov_b32_e32 v40, v102
	v_mov_b32_e32 v41, v103
	s_waitcnt lgkmcnt(8)
	v_mfma_f32_16x16x32_bf16 v[68:71], v[166:169], v[134:137], v[68:71]
	s_nop 0
	s_waitcnt lgkmcnt(7)
	v_mov_b32_e32 v74, v170
	v_mov_b32_e32 v75, v171
	v_mov_b32_e32 v138, v172
	v_mov_b32_e32 v139, v173
	v_mfma_f32_16x16x32_bf16 v[72:75], v[72:75], v[134:137], v[76:79]
	s_nop 2
	s_nop 0
	s_waitcnt lgkmcnt(6)
	v_mfma_f32_16x16x32_bf16 v[76:79], v[174:177], v[134:137], v[126:129]
	s_nop 2
	s_nop 0
	s_waitcnt lgkmcnt(5)
	v_mov_b32_e32 v132, v178
	v_mov_b32_e32 v133, v179
	v_mov_b32_e32 v126, v180
	v_mov_b32_e32 v127, v181
	v_mfma_f32_16x16x32_bf16 v[64:67], v[130:133], v[134:137], v[64:67]
	s_nop 0
	v_cvt_pk_bf16_f32 v130, v62, v63
	v_cvt_pk_bf16_f32 v131, v59, v143
	v_cvt_pk_bf16_f32 v132, v61, v144
	v_cvt_pk_bf16_f32 v133, v145, v146
	s_nop 0
	s_waitcnt lgkmcnt(4)
	v_mfma_f32_16x16x32_bf16 v[68:71], v[182:185], v[130:133], v[68:71]
	s_nop 0
	s_waitcnt lgkmcnt(2)
	v_mov_b32_e32 v140, v190
	v_mov_b32_e32 v141, v191
	v_mfma_f32_16x16x32_bf16 v[58:61], v[186:189], v[54:57], v[68:71]
	s_nop 0
	v_mfma_f32_16x16x32_bf16 v[72:75], v[138:141], v[130:133], v[72:75]
	s_nop 0
	s_waitcnt lgkmcnt(1)
	v_mfma_f32_16x16x32_bf16 v[76:79], v[196:199], v[130:133], v[76:79]
	s_nop 0
	s_waitcnt lgkmcnt(0)
	v_mov_b32_e32 v128, v200
	v_mov_b32_e32 v129, v201
	s_nop 1
	v_mfma_f32_16x16x32_bf16 v[62:65], v[126:129], v[130:133], v[64:67]
	v_mov_b32_e32 v126, v192
	s_nop 1
	ds_read2_b64 v[66:69], v148 offset0:124 offset1:128
	ds_read2_b64 v[204:207], v44 offset0:216 offset1:220
	ds_read2_b64 v[208:211], v45 offset0:60 offset1:64
	v_mov_b32_e32 v127, v193
	s_waitcnt lgkmcnt(2)
	v_mov_b32_e32 v128, v66
	v_mov_b32_e32 v129, v67
	s_nop 1
	v_mfma_f32_16x16x32_bf16 v[70:73], v[126:129], v[54:57], v[72:75]
	s_nop 0
	v_mov_b32_e32 v44, v100
	s_waitcnt lgkmcnt(1)
	v_mfma_f32_16x16x32_bf16 v[74:77], v[204:207], v[54:57], v[76:79]
	s_nop 2
	s_nop 0
	v_mov_b32_e32 v126, v202
	v_mov_b32_e32 v127, v203
	v_mov_b32_e32 v45, v101
	s_waitcnt lgkmcnt(0)
	v_mov_b32_e32 v128, v208
	v_mov_b32_e32 v129, v209
	s_nop 1
	v_mfma_f32_16x16x32_bf16 v[52:55], v[126:129], v[54:57], v[62:65]
	s_nop 2
	v_cvt_pk_bf16_f32 v62, v22, v23
	v_mov_b32_e32 v22, v68
	v_mov_b32_e32 v23, v69
	v_cvt_pk_bf16_f32 v63, v26, v27
	v_cvt_pk_bf16_f32 v64, v48, v49
	v_cvt_pk_bf16_f32 v65, v50, v51
	v_mov_b32_e32 v26, v210
	v_mov_b32_e32 v27, v211
	v_mfma_f32_16x16x32_bf16 v[48:51], v[22:25], v[62:65], v[70:73]
	v_div_scale_f32 v22, s[20:21], v47, v47, 1.0
	v_rcp_f32_e32 v23, v22
	v_mfma_f32_16x16x32_bf16 v[52:55], v[26:29], v[62:65], v[52:55]
	s_waitcnt vmcnt(0)
	v_mov_b64_e32 v[72:73], v[32:33]
	v_mov_b64_e32 v[70:71], v[30:31]
	v_fma_f32 v26, -v22, v23, 1.0
	v_fmac_f32_e32 v23, v26, v23
	v_div_scale_f32 v26, vcc, 1.0, v47, 1.0
	v_mul_f32_e32 v27, v26, v23
	v_fma_f32 v56, -v22, v27, v26
	v_mfma_f32_16x16x32_bf16 v[42:45], v[42:45], v[62:65], v[58:61]
	v_fmac_f32_e32 v27, v56, v23
	v_fma_f32 v22, -v22, v27, v26
	v_div_fmas_f32 v22, v22, v23, v27
	v_mfma_f32_16x16x32_bf16 v[38:41], v[38:41], v[62:65], v[74:77]
	v_div_fixup_f32 v22, v22, v47, 1.0
	s_nop 2
	v_pk_mul_f32 v[42:43], v[22:23], v[42:43] op_sel_hi:[0,1]
	v_pk_mul_f32 v[44:45], v[22:23], v[44:45] op_sel_hi:[0,1]
	v_mad_i64_i32 v[26:27], s[20:21], v46, s34, v[82:83]
	v_cvt_pk_bf16_f32 v42, v42, v43
	v_pk_mul_f32 v[38:39], v[22:23], v[38:39] op_sel_hi:[0,1]
	v_pk_mul_f32 v[40:41], v[22:23], v[40:41] op_sel_hi:[0,1]
	v_cvt_pk_bf16_f32 v43, v44, v45
	v_cvt_pk_bf16_f32 v38, v38, v39
	v_cvt_pk_bf16_f32 v39, v40, v41
	global_store_dwordx2 v[26:27], v[42:43], off
	v_pk_mul_f32 v[42:43], v[22:23], v[48:49] op_sel_hi:[0,1]
	v_pk_mul_f32 v[44:45], v[22:23], v[50:51] op_sel_hi:[0,1]
	global_store_dwordx2 v[26:27], v[38:39], off offset:64
	v_pk_mul_f32 v[38:39], v[22:23], v[52:53] op_sel_hi:[0,1]
	v_pk_mul_f32 v[22:23], v[22:23], v[54:55] op_sel_hi:[0,1]
	v_cvt_pk_bf16_f32 v38, v38, v39
	v_cvt_pk_bf16_f32 v39, v22, v23
	global_store_dwordx2 v[26:27], v[38:39], off offset:96
	v_mov_b64_e32 v[40:41], v[36:37]
	v_cvt_pk_bf16_f32 v42, v42, v43
	v_cvt_pk_bf16_f32 v43, v44, v45
	v_mov_b64_e32 v[38:39], v[34:35]
	global_store_dwordx2 v[26:27], v[42:43], off offset:32
	s_cbranch_scc0 .LBB0_429

; __device__ __forceinline__ f32x4 mfma32(bf16x8 a, bf16x8 b, f32x4 c) { return __builtin_amdgcn_mfma_f32_16x16x32_bf16(a, b, c, 0, 0, 0); }
; __device__ __forceinline__ void attn_unit(const Ptrs& P, int l, int b, int gk, int n, unsigned char* lds, int tid, bool dost) {
;     ...
;         for (int kt = 0; kt < 9; ++kt) { const unsigned char* kp = lds + AT_KS + (16 * (qs + kt) + lc) * 144 + 16 * g;
;             const bf16x8 a0 = *(const bf16x8*)kp, a1 = *(const bf16x8*)(kp + 64);
;             f32x4 z = {0.f, 0.f, 0.f, 0.f}; z = mfma32(a0, q0, z); st[kt] = mfma32(a1, q1, z); }
;         { const unsigned char* kp = lds + AT_KM + lc * 144 + 16 * g; const bf16x8 a0 = *(const bf16x8*)kp, a1 = *(const bf16x8*)(kp + 64);
;             f32x4 z = {0.f, 0.f, 0.f, 0.f}; z = mfma32(a0, q0, z); st[9] = mfma32(a1, q1, z); }
;         float mx = sink;
; #pragma unroll
;         for (int kt = 0; kt < 9; ++kt)
; #pragma unroll
;             for (int r = 0; r < 4; ++r) { const int dist = 128 + lc - 16 * kt - 4 * g - r; const int j = 16 * (qs + kt) + 4 * g + r;
;                 const bool valid = (dist >= 0) && (dist < 128) && (n >= 1) && (n >= 2 || j >= 128);
;                 const float lg = valid ? (st[kt][r] * 0.125f + hb[w * 128 + (dist & 127)]) : NEGV; st[kt][r] = lg; mx = fmaxf(mx, lg); }
.LBB0_323:
	v_add_u32_e32 v22, 0, v118
	ds_read_b128 v[150:153], v22
	ds_read_b128 v[154:157], v22 offset:64
	ds_read_b128 v[158:161], v22 offset:2304
	ds_read_b128 v[162:165], v22 offset:2368
	ds_read_b128 v[166:169], v22 offset:4608
	ds_read_b128 v[170:173], v22 offset:4672
	ds_read_b128 v[174:177], v22 offset:6912
	ds_read_b128 v[178:181], v22 offset:6976
	ds_read_b128 v[182:185], v22 offset:9216
	ds_read_b128 v[186:189], v22 offset:9280
	ds_read_b128 v[190:193], v22 offset:11520
	ds_read_b128 v[196:199], v22 offset:11584
	ds_read_b128 v[200:203], v22 offset:13824
	s_nop 0
	ds_read_b128 v[204:207], v22 offset:13888
	s_waitcnt lgkmcnt(13)
	v_mfma_f32_16x16x32_bf16 v[42:45], v[150:153], v[38:41], 0
	s_waitcnt lgkmcnt(12)
	v_mfma_f32_16x16x32_bf16 v[78:81], v[154:157], v[70:73], v[42:45]
	s_nop 5
	s_nop 0
	ds_read_b128 v[208:211], v22 offset:16128
	s_nop 0
	ds_read_b128 v[214:217], v22 offset:16192
	s_waitcnt lgkmcnt(13)
	v_mfma_f32_16x16x32_bf16 v[42:45], v[158:161], v[38:41], 0
	s_waitcnt lgkmcnt(12)
	v_mfma_f32_16x16x32_bf16 v[74:77], v[162:165], v[70:73], v[42:45]
	s_nop 5
	s_nop 0
	ds_read_b128 v[218:221], v22 offset:18432
	s_nop 0
	ds_read_b128 v[222:225], v22 offset:18496
	s_waitcnt lgkmcnt(13)
	v_mfma_f32_16x16x32_bf16 v[42:45], v[166:169], v[38:41], 0
	s_waitcnt lgkmcnt(12)
	v_mfma_f32_16x16x32_bf16 v[66:69], v[170:173], v[70:73], v[42:45]
	s_nop 5
	s_nop 0
	s_nop 0
	s_waitcnt lgkmcnt(11)
	v_mfma_f32_16x16x32_bf16 v[42:45], v[174:177], v[38:41], 0
	s_waitcnt lgkmcnt(10)
	v_mfma_f32_16x16x32_bf16 v[62:65], v[178:181], v[70:73], v[42:45]
	s_nop 5
	s_nop 0
	s_nop 0
	s_waitcnt lgkmcnt(9)
	v_mfma_f32_16x16x32_bf16 v[42:45], v[182:185], v[38:41], 0
	s_waitcnt lgkmcnt(8)
	v_mfma_f32_16x16x32_bf16 v[58:61], v[186:189], v[70:73], v[42:45]
	s_nop 5
	s_nop 0
	s_nop 0
	s_waitcnt lgkmcnt(7)
	v_mfma_f32_16x16x32_bf16 v[42:45], v[190:193], v[38:41], 0
	s_waitcnt lgkmcnt(6)
	v_mfma_f32_16x16x32_bf16 v[54:57], v[196:199], v[70:73], v[42:45]
	s_nop 5
	s_nop 0
	s_nop 0
	s_waitcnt lgkmcnt(5)
	v_mfma_f32_16x16x32_bf16 v[42:45], v[200:203], v[38:41], 0
	s_waitcnt lgkmcnt(4)
	v_mfma_f32_16x16x32_bf16 v[50:53], v[204:207], v[70:73], v[42:45]
	s_nop 5
	s_nop 0
	s_nop 0
	s_waitcnt lgkmcnt(3)
	v_mfma_f32_16x16x32_bf16 v[42:45], v[208:211], v[38:41], 0
	s_waitcnt lgkmcnt(2)
	v_mfma_f32_16x16x32_bf16 v[46:49], v[214:217], v[70:73], v[42:45]
	s_nop 5
	s_nop 0
	s_nop 0
	s_waitcnt lgkmcnt(1)
	v_mfma_f32_16x16x32_bf16 v[42:45], v[218:221], v[38:41], 0
	v_mfma_f32_16x16x32_bf16 v[38:41], v[10:13], v[38:41], 0
	s_waitcnt lgkmcnt(0)
	v_mfma_f32_16x16x32_bf16 v[42:45], v[222:225], v[70:73], v[42:45]
	v_mfma_f32_16x16x32_bf16 v[38:41], v[18:21], v[70:73], v[38:41]
	v_mov_b32_e32 v70, 0xf149f2ca
	v_mov_b32_e32 v73, 0xf149f2ca
	s_and_saveexec_b64 s[12:13], s[8:9]
	s_cbranch_execz .LBB0_325
	ds_read_b32 v73, v111 offset:512
	s_waitcnt lgkmcnt(0)
	v_fmac_f32_e32 v73, 0x3e000000, v78

; __device__ __forceinline__ unsigned pk2(float lo, float hi) { f32x2_t v = {lo, hi}; bf16x2_t b = __builtin_convertvector(v, bf16x2_t); return __builtin_bit_cast(unsigned, b); }
; __device__ __forceinline__ f32x4 mfma16(bf16x4 a, bf16x4 b, f32x4 c) { return __builtin_amdgcn_mfma_f32_16x16x16bf16_1k(a, b, c, 0, 0, 0); }
; __device__ __forceinline__ bf16x4 pack4(f32x4 v) { u32x2 w; w.x = pk2(v[0], v[1]); w.y = pk2(v[2], v[3]); return __builtin_bit_cast(bf16x4, w); }
; __device__ __forceinline__ void hg_unit(const Ptrs& P, int l, int b, int hd, int ch, unsigned char* lds, int tid) {
;     ...
;     for (int j = 0; j < 8; ++j) {
;         if (j < nsub) {
;             const bf16x4 vf = *(const bf16x4*)(Vt + (j * 16 + lc) * 20 + 4 * g);
;             const bf16x4 atj = *(const bf16x4*)HG_ATT_SLOT(j);
;             f32x4 o = mfma16(vf, atj, (f32x4){0.f, 0.f, 0.f, 0.f});
;             if (j > 0) {
; #pragma unroll
;                 for (int kt = 0; kt < 8; ++kt) { const bf16x4 qf = *(const bf16x4*)(Qb + (16 * j + lc) * 136 + 16 * kt + 4 * g); o = mfma16(pack4(S[kt]), qf, o); } }
;             { u32x2 wv; wv.x = pk2(o[0], o[1]); wv.y = pk2(o[2], o[3]); *(u32x2*)(PJ + (row0 + 16 * j + lc) * PW + C_HI + hd * 128 + 16 * w + 4 * g) = wv; }
; #pragma unroll
;             for (int kt = 0; kt < 8; ++kt) { const f32x4 eb = *(const f32x4*)(EBE + j * 128 + 16 * kt + 4 * g);
;                 const bf16x4 kf = *(const bf16x4*)(Ket + (j * 128 + 16 * kt + lc) * 20 + 4 * g);
;                 S[kt] = mfma16(kf, vf, S[kt] * eb); }
.LBB0_603:
	s_or_b64 exec, exec, s[4:5]
	s_nop 0
	v_lshlrev_b32_e32 v18, 3, v13
	v_add_u32_e32 v58, v32, v18
	v_lshl_add_u32 v13, v13, 4, 0
	v_add_u32_e32 v17, 0x1b000, v13
	v_mad_u32_u24 v13, v48, 40, v58
	ds_read_b64 v[150:151], v13
	v_readlane_b32 s3, v255, 27
	s_nop 0
	ds_read_b128 v[22:25], v17 offset:64
	v_cmp_gt_u32_e32 vcc, 32, v108
	v_mov_b32_e32 v10, s3
	v_bfe_u32 v11, v98, 1, 4
	v_cndmask_b32_e64 v10, v10, 0, vcc
	v_mul_u32_u24_e32 v11, 0x110, v11
	v_add3_u32 v61, v10, v11, v12
	ds_read_b64 v[152:153], v61 offset:256
	v_mov_b32_e32 v49, v16
	s_waitcnt lgkmcnt(0)
	v_mfma_f32_16x16x16_bf16 v[10:13], v[150:151], v[152:153], 0
	v_lshl_add_u64 v[20:21], s[44:45], 0, v[48:49]
	v_mad_u64_u32 v[52:53], s[4:5], v20, s34, v[86:87]
	v_mad_i32_i24 v53, v21, s34, v53
	s_nop 4
	v_cvt_pk_bf16_f32 v10, v10, v11
	v_cvt_pk_bf16_f32 v11, v12, v13
	v_lshl_add_u64 v[12:13], v[52:53], 0, s[96:97]
	v_lshl_add_u64 v[56:57], v[46:47], 1, v[12:13]
	v_mov_b32_e32 v19, v16
	v_lshl_add_u64 v[12:13], v[56:57], 0, v[18:19]
	s_movk_i32 s3, 0x3000
	v_mul_u32_u24_e32 v60, 40, v48
	v_add_co_u32_e32 v12, vcc, s3, v12
	v_readlane_b32 s3, v255, 25
	v_add_u32_e32 v59, 0, v18
	v_addc_co_u32_e32 v13, vcc, 0, v13, vcc
	v_add3_u32 v49, s3, v18, v60
	ds_read2_b64 v[154:157], v49 offset1:80
	global_store_dwordx2 v[12:13], v[10:11], off offset:2560
	ds_read_b128 v[10:13], v17
	v_pk_mul_f32 v[24:25], v[24:25], 0 op_sel_hi:[1,0]
	v_pk_mul_f32 v[22:23], v[22:23], 0 op_sel_hi:[1,0]
	v_add_u32_e32 v34, 0x800, v49
	v_add_u32_e32 v44, 0xc00, v49
	s_waitcnt lgkmcnt(0)
	v_pk_mul_f32 v[12:13], v[12:13], 0 op_sel_hi:[1,0]
	v_pk_mul_f32 v[10:11], v[10:11], 0 op_sel_hi:[1,0]
	s_and_b64 vcc, exec, s[38:39]
	v_lshlrev_b32_e32 v50, 1, v50
	v_mfma_f32_16x16x16_bf16 v[10:13], v[154:155], v[150:151], v[10:13]
	v_mfma_f32_16x16x16_bf16 v[18:21], v[156:157], v[150:151], v[22:25]
	s_nop 2
	ds_read_b128 v[22:25], v17 offset:128
	ds_read2_b64 v[158:161], v49 offset0:160 offset1:240
	ds_read_b128 v[30:33], v17 offset:192
	ds_read_b128 v[38:41], v17 offset:320
	ds_read2_b64 v[162:165], v34 offset0:64 offset1:144
	s_waitcnt lgkmcnt(4)
	v_pk_mul_f32 v[24:25], v[24:25], 0 op_sel_hi:[1,0]
	v_pk_mul_f32 v[22:23], v[22:23], 0 op_sel_hi:[1,0]
	s_waitcnt lgkmcnt(2)
	v_pk_mul_f32 v[32:33], v[32:33], 0 op_sel_hi:[1,0]
	v_pk_mul_f32 v[30:31], v[30:31], 0 op_sel_hi:[1,0]
	v_mfma_f32_16x16x16_bf16 v[22:25], v[158:159], v[150:151], v[22:25]
	ds_read2_b64 v[62:65], v44 offset0:96 offset1:176
	s_waitcnt lgkmcnt(2)
	v_pk_mul_f32 v[40:41], v[40:41], 0 op_sel_hi:[1,0]
	v_pk_mul_f32 v[38:39], v[38:39], 0 op_sel_hi:[1,0]
	v_mfma_f32_16x16x16_bf16 v[26:29], v[160:161], v[150:151], v[30:33]
	ds_read_b128 v[66:69], v17 offset:448
	s_waitcnt lgkmcnt(0)
	v_pk_mul_f32 v[68:69], v[68:69], 0 op_sel_hi:[1,0]
	ds_read_b128 v[30:33], v17 offset:256
	v_pk_mul_f32 v[66:67], v[66:67], 0 op_sel_hi:[1,0]
	s_waitcnt lgkmcnt(0)
	v_pk_mul_f32 v[32:33], v[32:33], 0 op_sel_hi:[1,0]
	v_pk_mul_f32 v[30:31], v[30:31], 0 op_sel_hi:[1,0]
	s_nop 1
	v_mfma_f32_16x16x16_bf16 v[30:33], v[162:163], v[150:151], v[30:33]
	v_mfma_f32_16x16x16_bf16 v[34:37], v[164:165], v[150:151], v[38:41]
	s_nop 2
	ds_read_b128 v[38:41], v17 offset:384
	s_waitcnt lgkmcnt(0)
	v_pk_mul_f32 v[40:41], v[40:41], 0 op_sel_hi:[1,0]
	v_pk_mul_f32 v[38:39], v[38:39], 0 op_sel_hi:[1,0]
	s_nop 1
	v_mfma_f32_16x16x16_bf16 v[38:41], v[62:63], v[150:151], v[38:41]
	v_mfma_f32_16x16x16_bf16 v[42:45], v[64:65], v[150:151], v[66:69]
	s_cbranch_vccz .LBB0_613
	s_and_b64 vcc, exec, s[38:39]
	s_cbranch_vccz .LBB0_614

; __device__ __forceinline__ unsigned pk2(float lo, float hi) { f32x2_t v = {lo, hi}; bf16x2_t b = __builtin_convertvector(v, bf16x2_t); return __builtin_bit_cast(unsigned, b); }
; __device__ __forceinline__ f32x4 mfma16(bf16x4 a, bf16x4 b, f32x4 c) { return __builtin_amdgcn_mfma_f32_16x16x16bf16_1k(a, b, c, 0, 0, 0); }
; __device__ __forceinline__ bf16x4 pack4(f32x4 v) { u32x2 w; w.x = pk2(v[0], v[1]); w.y = pk2(v[2], v[3]); return __builtin_bit_cast(bf16x4, w); }
; __device__ __forceinline__ void hg_unit(const Ptrs& P, int l, int b, int hd, int ch, unsigned char* lds, int tid) {
;     ...
;     for (int j = 0; j < 8; ++j) {
;         if (j < nsub) {
;             const bf16x4 vf = *(const bf16x4*)(Vt + (j * 16 + lc) * 20 + 4 * g);
;             const bf16x4 atj = *(const bf16x4*)HG_ATT_SLOT(j);
;             f32x4 o = mfma16(vf, atj, (f32x4){0.f, 0.f, 0.f, 0.f});
;             if (j > 0) {
; #pragma unroll
;                 for (int kt = 0; kt < 8; ++kt) { const bf16x4 qf = *(const bf16x4*)(Qb + (16 * j + lc) * 136 + 16 * kt + 4 * g); o = mfma16(pack4(S[kt]), qf, o); } }
;             { u32x2 wv; wv.x = pk2(o[0], o[1]); wv.y = pk2(o[2], o[3]); *(u32x2*)(PJ + (row0 + 16 * j + lc) * PW + C_HI + hd * 128 + 16 * w + 4 * g) = wv; }
; #pragma unroll
;             for (int kt = 0; kt < 8; ++kt) { const f32x4 eb = *(const f32x4*)(EBE + j * 128 + 16 * kt + 4 * g);
;                 const bf16x4 kf = *(const bf16x4*)(Ket + (j * 128 + 16 * kt + lc) * 20 + 4 * g);
;                 S[kt] = mfma16(kf, vf, S[kt] * eb); }
.LBB0_610:
	v_add_u32_e32 v54, v60, v58
	ds_read_b64 v[54:55], v54 offset:4480
	ds_read_b64 v[150:151], v61 offset:30720
	v_or_b32_e32 v51, 0x70, v48
	v_mad_u32_u24 v51, v51, s26, v59
	ds_read2_b64 v[152:155], v51 offset1:4
	ds_read2_b64 v[156:159], v51 offset0:8 offset1:12
	ds_read2_b64 v[160:163], v51 offset0:16 offset1:20
	ds_read2_b64 v[164:167], v51 offset0:24 offset1:28
	ds_read_b128 v[168:171], v17 offset:3584
	v_cvt_pk_bf16_f32 v64, v10, v11
	v_cvt_pk_bf16_f32 v65, v12, v13
	s_waitcnt lgkmcnt(5)
	v_mfma_f32_16x16x16_bf16 v[60:63], v[54:55], v[150:151], 0
	s_nop 0
	v_lshl_add_u64 v[52:53], v[52:53], 0, s[96:97]
	v_lshl_add_u64 v[46:47], v[46:47], 1, v[52:53]
	s_mov_b32 s3, 0x1d1000
	s_waitcnt lgkmcnt(4)
	v_mfma_f32_16x16x16_bf16 v[60:63], v[64:65], v[152:153], v[60:63]
	v_cvt_pk_bf16_f32 v56, v18, v19
	v_cvt_pk_bf16_f32 v57, v20, v21
	v_cvt_pk_bf16_f32 v64, v22, v23
	v_cvt_pk_bf16_f32 v65, v24, v25
	v_mfma_f32_16x16x16_bf16 v[56:59], v[56:57], v[154:155], v[60:63]
	s_nop 2
	s_nop 0
	s_waitcnt lgkmcnt(3)
	v_mfma_f32_16x16x16_bf16 v[56:59], v[64:65], v[156:157], v[56:59]
	v_cvt_pk_bf16_f32 v60, v26, v27
	v_cvt_pk_bf16_f32 v61, v28, v29
	v_cvt_pk_bf16_f32 v64, v30, v31
	v_cvt_pk_bf16_f32 v65, v32, v33
	v_mfma_f32_16x16x16_bf16 v[56:59], v[60:61], v[158:159], v[56:59]
	s_nop 0
	s_waitcnt lgkmcnt(2)
	v_mfma_f32_16x16x16_bf16 v[56:59], v[64:65], v[160:161], v[56:59]
	v_cvt_pk_bf16_f32 v60, v34, v35
	v_cvt_pk_bf16_f32 v61, v36, v37
	v_cvt_pk_bf16_f32 v64, v38, v39
	v_cvt_pk_bf16_f32 v65, v40, v41
	v_mfma_f32_16x16x16_bf16 v[56:59], v[60:61], v[162:163], v[56:59]
	s_nop 0
	v_mov_b32_e32 v51, v16
	v_lshl_add_u64 v[46:47], v[46:47], 0, v[50:51]
	s_waitcnt lgkmcnt(1)
	v_mfma_f32_16x16x16_bf16 v[56:59], v[64:65], v[164:165], v[56:59]
	v_cvt_pk_bf16_f32 v60, v42, v43
	v_cvt_pk_bf16_f32 v61, v44, v45
	v_add_co_u32_e32 v46, vcc, s3, v46
	s_nop 0
	v_mfma_f32_16x16x16_bf16 v[56:59], v[60:61], v[166:167], v[56:59]
	v_addc_co_u32_e32 v47, vcc, 0, v47, vcc
	s_nop 6
	v_cvt_pk_bf16_f32 v56, v56, v57
	v_cvt_pk_bf16_f32 v57, v58, v59
	global_store_dwordx2 v[46:47], v[56:57], off offset:2560
	s_nop 0
	v_add_u32_e32 v46, 0x8800, v49
	ds_read2_b64 v[172:175], v46 offset0:128 offset1:208
	ds_read_b128 v[176:179], v17 offset:3648
	ds_read_b128 v[180:183], v17 offset:3712
	v_add_u32_e32 v46, 0x9000, v49
	ds_read2_b64 v[184:187], v46 offset0:32 offset1:112
	ds_read_b128 v[188:191], v17 offset:3776
	ds_read_b128 v[196:199], v17 offset:3840
	s_waitcnt lgkmcnt(6)
	v_pk_mul_f32 v[12:13], v[12:13], v[170:171]
	v_pk_mul_f32 v[10:11], v[10:11], v[168:169]
	s_nop 0
	s_waitcnt lgkmcnt(4)
	v_pk_mul_f32 v[20:21], v[20:21], v[178:179]
	v_pk_mul_f32 v[18:19], v[18:19], v[176:177]
	s_nop 0
	v_mfma_f32_16x16x16_bf16 v[10:13], v[172:173], v[54:55], v[10:13]
	s_waitcnt lgkmcnt(3)
	v_pk_mul_f32 v[24:25], v[24:25], v[182:183]
	v_mfma_f32_16x16x16_bf16 v[18:21], v[174:175], v[54:55], v[18:21]
	s_nop 0
	v_pk_mul_f32 v[22:23], v[22:23], v[180:181]
	s_nop 0
	v_add_u32_e32 v46, 0x9400, v49
	ds_read2_b64 v[200:203], v46 offset0:64 offset1:144
	ds_read_b128 v[204:207], v17 offset:3904
	ds_read_b128 v[208:211], v17 offset:3968
	s_waitcnt lgkmcnt(5)
	v_mfma_f32_16x16x16_bf16 v[22:25], v[184:185], v[54:55], v[22:25]
	s_waitcnt lgkmcnt(4)
	v_pk_mul_f32 v[28:29], v[28:29], v[190:191]
	v_pk_mul_f32 v[26:27], v[26:27], v[188:189]
	s_nop 0
	s_waitcnt lgkmcnt(3)
	v_pk_mul_f32 v[32:33], v[32:33], v[198:199]
	v_mfma_f32_16x16x16_bf16 v[26:29], v[186:187], v[54:55], v[26:29]
	s_nop 0
	v_pk_mul_f32 v[30:31], v[30:31], v[196:197]
	s_nop 0
	v_add_u32_e32 v46, 0x9800, v49
	s_waitcnt lgkmcnt(2)
	v_mfma_f32_16x16x16_bf16 v[30:33], v[200:201], v[54:55], v[30:33]
	s_waitcnt lgkmcnt(1)
	v_pk_mul_f32 v[36:37], v[36:37], v[206:207]
	v_pk_mul_f32 v[34:35], v[34:35], v[204:205]
	s_nop 0
	s_waitcnt lgkmcnt(0)
	v_pk_mul_f32 v[40:41], v[40:41], v[210:211]
	v_mfma_f32_16x16x16_bf16 v[34:37], v[202:203], v[54:55], v[34:37]
	ds_read2_b64 v[60:63], v46 offset0:96 offset1:176
	v_pk_mul_f32 v[38:39], v[38:39], v[208:209]
	ds_read_b128 v[56:59], v17 offset:4032
	s_waitcnt lgkmcnt(0)
	v_pk_mul_f32 v[44:45], v[44:45], v[58:59]
	v_pk_mul_f32 v[42:43], v[42:43], v[56:57]
	v_mfma_f32_16x16x16_bf16 v[38:41], v[60:61], v[54:55], v[38:41]
	s_nop 0
	v_mfma_f32_16x16x16_bf16 v[42:45], v[62:63], v[54:55], v[42:45]

; __device__ __forceinline__ unsigned pk2(float lo, float hi) { f32x2_t v = {lo, hi}; bf16x2_t b = __builtin_convertvector(v, bf16x2_t); return __builtin_bit_cast(unsigned, b); }
; __device__ __forceinline__ f32x4 mfma16(bf16x4 a, bf16x4 b, f32x4 c) { return __builtin_amdgcn_mfma_f32_16x16x16bf16_1k(a, b, c, 0, 0, 0); }
; __device__ __forceinline__ bf16x4 pack4(f32x4 v) { u32x2 w; w.x = pk2(v[0], v[1]); w.y = pk2(v[2], v[3]); return __builtin_bit_cast(bf16x4, w); }
; __device__ __forceinline__ void hg_unit(const Ptrs& P, int l, int b, int hd, int ch, unsigned char* lds, int tid) {
;     ...
;     for (int j = 0; j < 8; ++j) {
;         if (j < nsub) {
;             const bf16x4 vf = *(const bf16x4*)(Vt + (j * 16 + lc) * 20 + 4 * g);
;             const bf16x4 atj = *(const bf16x4*)HG_ATT_SLOT(j);
;             f32x4 o = mfma16(vf, atj, (f32x4){0.f, 0.f, 0.f, 0.f});
;             if (j > 0) {
; #pragma unroll
;                 for (int kt = 0; kt < 8; ++kt) { const bf16x4 qf = *(const bf16x4*)(Qb + (16 * j + lc) * 136 + 16 * kt + 4 * g); o = mfma16(pack4(S[kt]), qf, o); } }
;             { u32x2 wv; wv.x = pk2(o[0], o[1]); wv.y = pk2(o[2], o[3]); *(u32x2*)(PJ + (row0 + 16 * j + lc) * PW + C_HI + hd * 128 + 16 * w + 4 * g) = wv; }
; #pragma unroll
;             for (int kt = 0; kt < 8; ++kt) { const f32x4 eb = *(const f32x4*)(EBE + j * 128 + 16 * kt + 4 * g);
;                 const bf16x4 kf = *(const bf16x4*)(Ket + (j * 128 + 16 * kt + lc) * 20 + 4 * g);
;                 S[kt] = mfma16(kf, vf, S[kt] * eb); }
.LBB0_613:
	v_or_b32_e32 v51, 16, v48
	v_mad_u32_u24 v54, v51, 40, v58
	ds_read_b64 v[54:55], v54
	ds_read_b64 v[150:151], v61 offset:4608
	v_mad_u32_u24 v51, v51, s26, v59
	ds_read2_b64 v[152:155], v51 offset1:4
	ds_read2_b64 v[156:159], v51 offset0:8 offset1:12
	ds_read2_b64 v[160:163], v51 offset0:16 offset1:20
	ds_read2_b64 v[164:167], v51 offset0:24 offset1:28
	ds_read_b128 v[168:171], v17 offset:512
	v_cvt_pk_bf16_f32 v70, v10, v11
	v_cvt_pk_bf16_f32 v71, v12, v13
	s_nop 0
	s_waitcnt lgkmcnt(5)
	v_mfma_f32_16x16x16_bf16 v[62:65], v[54:55], v[150:151], 0
	s_mov_b32 s3, 0x45000
	s_waitcnt lgkmcnt(4)
	v_mfma_f32_16x16x16_bf16 v[62:65], v[70:71], v[152:153], v[62:65]
	v_cvt_pk_bf16_f32 v66, v18, v19
	v_cvt_pk_bf16_f32 v67, v20, v21
	v_cvt_pk_bf16_f32 v70, v22, v23
	v_cvt_pk_bf16_f32 v71, v24, v25
	v_mfma_f32_16x16x16_bf16 v[62:65], v[66:67], v[154:155], v[62:65]
	s_nop 0
	s_waitcnt lgkmcnt(3)
	v_mfma_f32_16x16x16_bf16 v[62:65], v[70:71], v[156:157], v[62:65]
	v_cvt_pk_bf16_f32 v66, v26, v27
	v_cvt_pk_bf16_f32 v67, v28, v29
	v_cvt_pk_bf16_f32 v70, v30, v31
	v_cvt_pk_bf16_f32 v71, v32, v33
	v_mfma_f32_16x16x16_bf16 v[62:65], v[66:67], v[158:159], v[62:65]
	s_nop 0
	s_waitcnt lgkmcnt(2)
	v_mfma_f32_16x16x16_bf16 v[62:65], v[70:71], v[160:161], v[62:65]
	v_cvt_pk_bf16_f32 v66, v34, v35
	v_cvt_pk_bf16_f32 v67, v36, v37
	v_cvt_pk_bf16_f32 v70, v38, v39
	v_cvt_pk_bf16_f32 v71, v40, v41
	v_mfma_f32_16x16x16_bf16 v[62:65], v[66:67], v[162:163], v[62:65]
	s_nop 0
	v_mov_b32_e32 v51, v16
	v_lshl_add_u64 v[56:57], v[56:57], 0, v[50:51]
	s_waitcnt lgkmcnt(1)
	v_mfma_f32_16x16x16_bf16 v[62:65], v[70:71], v[164:165], v[62:65]
	v_cvt_pk_bf16_f32 v66, v42, v43
	v_cvt_pk_bf16_f32 v67, v44, v45
	v_add_co_u32_e32 v56, vcc, s3, v56
	s_nop 0
	v_mfma_f32_16x16x16_bf16 v[62:65], v[66:67], v[166:167], v[62:65]
	v_addc_co_u32_e32 v57, vcc, 0, v57, vcc
	v_add_u32_e32 v51, 0x1000, v49
	ds_read2_b64 v[172:175], v51 offset0:128 offset1:208
	ds_read_b128 v[176:179], v17 offset:576
	ds_read_b128 v[180:183], v17 offset:640
	s_nop 5
	v_cvt_pk_bf16_f32 v62, v62, v63
	v_cvt_pk_bf16_f32 v63, v64, v65
	global_store_dwordx2 v[56:57], v[62:63], off offset:2560
	s_nop 0
	s_nop 0
	v_add_u32_e32 v51, 0x1800, v49
	ds_read2_b64 v[184:187], v51 offset0:32 offset1:112
	ds_read_b128 v[188:191], v17 offset:704
	ds_read_b128 v[196:199], v17 offset:768
	s_waitcnt lgkmcnt(6)
	v_pk_mul_f32 v[12:13], v[12:13], v[170:171]
	v_pk_mul_f32 v[10:11], v[10:11], v[168:169]
	s_nop 0
	s_waitcnt lgkmcnt(4)
	v_pk_mul_f32 v[20:21], v[20:21], v[178:179]
	v_pk_mul_f32 v[18:19], v[18:19], v[176:177]
	s_nop 0
	v_mfma_f32_16x16x16_bf16 v[10:13], v[172:173], v[54:55], v[10:13]
	s_waitcnt lgkmcnt(3)
	v_pk_mul_f32 v[24:25], v[24:25], v[182:183]
	v_mfma_f32_16x16x16_bf16 v[18:21], v[174:175], v[54:55], v[18:21]
	s_nop 0
	v_pk_mul_f32 v[22:23], v[22:23], v[180:181]
	s_nop 0
	v_add_u32_e32 v51, 0x1c00, v49
	ds_read2_b64 v[200:203], v51 offset0:64 offset1:144
	ds_read_b128 v[204:207], v17 offset:832
	ds_read_b128 v[208:211], v17 offset:896
	s_waitcnt lgkmcnt(5)
	v_mfma_f32_16x16x16_bf16 v[22:25], v[184:185], v[54:55], v[22:25]
	s_waitcnt lgkmcnt(4)
	v_pk_mul_f32 v[28:29], v[28:29], v[190:191]
	v_pk_mul_f32 v[26:27], v[26:27], v[188:189]
	s_nop 0
	s_waitcnt lgkmcnt(3)
	v_pk_mul_f32 v[32:33], v[32:33], v[198:199]
	v_mfma_f32_16x16x16_bf16 v[26:29], v[186:187], v[54:55], v[26:29]
	s_nop 0
	v_pk_mul_f32 v[30:31], v[30:31], v[196:197]
	s_nop 0
	v_add_u32_e32 v51, 0x2000, v49
	s_waitcnt lgkmcnt(2)
	v_mfma_f32_16x16x16_bf16 v[30:33], v[200:201], v[54:55], v[30:33]
	s_waitcnt lgkmcnt(1)
	v_pk_mul_f32 v[36:37], v[36:37], v[206:207]
	v_pk_mul_f32 v[34:35], v[34:35], v[204:205]
	s_nop 0
	s_waitcnt lgkmcnt(0)
	v_pk_mul_f32 v[40:41], v[40:41], v[210:211]
	v_mfma_f32_16x16x16_bf16 v[34:37], v[202:203], v[54:55], v[34:37]
	ds_read2_b64 v[66:69], v51 offset0:96 offset1:176
	v_pk_mul_f32 v[38:39], v[38:39], v[208:209]
	ds_read_b128 v[62:65], v17 offset:960
	s_waitcnt lgkmcnt(0)
	v_pk_mul_f32 v[44:45], v[44:45], v[64:65]
	v_pk_mul_f32 v[42:43], v[42:43], v[62:63]
	v_mfma_f32_16x16x16_bf16 v[38:41], v[66:67], v[54:55], v[38:41]
	s_nop 0
	v_mfma_f32_16x16x16_bf16 v[42:45], v[68:69], v[54:55], v[42:45]
	s_and_b64 vcc, exec, s[38:39]
	s_cbranch_vccnz .LBB0_605
; __device__ __forceinline__ unsigned pk2(float lo, float hi) { f32x2_t v = {lo, hi}; bf16x2_t b = __builtin_convertvector(v, bf16x2_t); return __builtin_bit_cast(unsigned, b); }
; __device__ __forceinline__ f32x4 mfma16(bf16x4 a, bf16x4 b, f32x4 c) { return __builtin_amdgcn_mfma_f32_16x16x16bf16_1k(a, b, c, 0, 0, 0); }
; __device__ __forceinline__ bf16x4 pack4(f32x4 v) { u32x2 w; w.x = pk2(v[0], v[1]); w.y = pk2(v[2], v[3]); return __builtin_bit_cast(bf16x4, w); }
; __device__ __forceinline__ void hg_unit(const Ptrs& P, int l, int b, int hd, int ch, unsigned char* lds, int tid) {
;     ...
;     for (int j = 0; j < 8; ++j) {
;         if (j < nsub) {
;             const bf16x4 vf = *(const bf16x4*)(Vt + (j * 16 + lc) * 20 + 4 * g);
;             const bf16x4 atj = *(const bf16x4*)HG_ATT_SLOT(j);
;             f32x4 o = mfma16(vf, atj, (f32x4){0.f, 0.f, 0.f, 0.f});
;             if (j > 0) {
; #pragma unroll
;                 for (int kt = 0; kt < 8; ++kt) { const bf16x4 qf = *(const bf16x4*)(Qb + (16 * j + lc) * 136 + 16 * kt + 4 * g); o = mfma16(pack4(S[kt]), qf, o); } }
;             { u32x2 wv; wv.x = pk2(o[0], o[1]); wv.y = pk2(o[2], o[3]); *(u32x2*)(PJ + (row0 + 16 * j + lc) * PW + C_HI + hd * 128 + 16 * w + 4 * g) = wv; }
; #pragma unroll
;             for (int kt = 0; kt < 8; ++kt) { const f32x4 eb = *(const f32x4*)(EBE + j * 128 + 16 * kt + 4 * g);
;                 const bf16x4 kf = *(const bf16x4*)(Ket + (j * 128 + 16 * kt + lc) * 20 + 4 * g);
;                 S[kt] = mfma16(kf, vf, S[kt] * eb); }
.LBB0_614:
	v_or_b32_e32 v51, 32, v48
	v_mad_u32_u24 v54, v51, 40, v58
	ds_read_b64 v[54:55], v54
	ds_read_b64 v[150:151], v61 offset:8960
	v_mad_u32_u24 v51, v51, s26, v59
	ds_read2_b64 v[152:155], v51 offset1:4
	ds_read2_b64 v[156:159], v51 offset0:8 offset1:12
	ds_read2_b64 v[160:163], v51 offset0:16 offset1:20
	ds_read2_b64 v[164:167], v51 offset0:24 offset1:28
	ds_read_b128 v[168:171], v17 offset:1024
	s_mov_b32 s3, 0x87000
	s_waitcnt lgkmcnt(5)
	v_mfma_f32_16x16x16_bf16 v[62:65], v[54:55], v[150:151], 0
	v_cvt_pk_bf16_f32 v56, v10, v11
	v_cvt_pk_bf16_f32 v57, v12, v13
	s_waitcnt lgkmcnt(4)
	s_nop 0
	v_mfma_f32_16x16x16_bf16 v[62:65], v[56:57], v[152:153], v[62:65]
	v_cvt_pk_bf16_f32 v56, v18, v19
	v_cvt_pk_bf16_f32 v57, v20, v21
	s_nop 1
	v_mfma_f32_16x16x16_bf16 v[62:65], v[56:57], v[154:155], v[62:65]
	s_nop 0
	v_cvt_pk_bf16_f32 v56, v22, v23
	v_cvt_pk_bf16_f32 v57, v24, v25
	s_waitcnt lgkmcnt(3)
	s_nop 0
	v_mfma_f32_16x16x16_bf16 v[62:65], v[56:57], v[156:157], v[62:65]
	v_cvt_pk_bf16_f32 v56, v26, v27
	v_cvt_pk_bf16_f32 v57, v28, v29
	s_nop 1
	v_mfma_f32_16x16x16_bf16 v[62:65], v[56:57], v[158:159], v[62:65]
	s_nop 0
	v_cvt_pk_bf16_f32 v56, v30, v31
	v_cvt_pk_bf16_f32 v57, v32, v33
	s_waitcnt lgkmcnt(2)
	s_nop 0
	v_mfma_f32_16x16x16_bf16 v[62:65], v[56:57], v[160:161], v[62:65]
	v_cvt_pk_bf16_f32 v56, v34, v35
	v_cvt_pk_bf16_f32 v57, v36, v37
	s_nop 1
	v_mfma_f32_16x16x16_bf16 v[62:65], v[56:57], v[162:163], v[62:65]
	s_nop 0
	v_cvt_pk_bf16_f32 v56, v38, v39
	v_cvt_pk_bf16_f32 v57, v40, v41
	v_mov_b32_e32 v51, v16
	s_waitcnt lgkmcnt(1)
	v_mfma_f32_16x16x16_bf16 v[62:65], v[56:57], v[164:165], v[62:65]
	v_cvt_pk_bf16_f32 v56, v42, v43
	v_cvt_pk_bf16_f32 v57, v44, v45
	s_nop 1
	v_mfma_f32_16x16x16_bf16 v[62:65], v[56:57], v[166:167], v[62:65]
	s_nop 7
	v_cvt_pk_bf16_f32 v56, v62, v63
	v_lshl_add_u64 v[62:63], v[52:53], 0, s[96:97]
	v_lshl_add_u64 v[62:63], v[46:47], 1, v[62:63]
	v_lshl_add_u64 v[62:63], v[62:63], 0, v[50:51]
	v_add_co_u32_e32 v62, vcc, s3, v62
	v_cvt_pk_bf16_f32 v57, v64, v65
	s_nop 0
	v_addc_co_u32_e32 v63, vcc, 0, v63, vcc
	global_store_dwordx2 v[62:63], v[56:57], off offset:2560
	s_nop 0
	v_add_u32_e32 v51, 0x2800, v49
	ds_read2_b64 v[172:175], v51 offset1:80
	ds_read_b128 v[176:179], v17 offset:1088
	ds_read_b128 v[180:183], v17 offset:1152
	ds_read2_b64 v[184:187], v51 offset0:160 offset1:240
	ds_read_b128 v[188:191], v17 offset:1216
	ds_read_b128 v[196:199], v17 offset:1280
	s_waitcnt lgkmcnt(6)
	v_pk_mul_f32 v[12:13], v[12:13], v[170:171]
	v_pk_mul_f32 v[10:11], v[10:11], v[168:169]
	s_nop 0
	s_waitcnt lgkmcnt(4)
	v_pk_mul_f32 v[20:21], v[20:21], v[178:179]
	v_pk_mul_f32 v[18:19], v[18:19], v[176:177]
	v_mfma_f32_16x16x16_bf16 v[10:13], v[172:173], v[54:55], v[10:13]
	s_nop 0
	v_mfma_f32_16x16x16_bf16 v[18:21], v[174:175], v[54:55], v[18:21]
	s_nop 0
	s_nop 0
	v_add_u32_e32 v51, 0x3000, v49
	ds_read2_b64 v[200:203], v51 offset0:64 offset1:144
	ds_read_b128 v[204:207], v17 offset:1344
	ds_read_b128 v[208:211], v17 offset:1408
	s_waitcnt lgkmcnt(6)
	v_pk_mul_f32 v[24:25], v[24:25], v[182:183]
	v_pk_mul_f32 v[22:23], v[22:23], v[180:181]
	s_nop 0
	s_waitcnt lgkmcnt(4)
	v_pk_mul_f32 v[28:29], v[28:29], v[190:191]
	v_pk_mul_f32 v[26:27], v[26:27], v[188:189]
	s_nop 0
	v_mfma_f32_16x16x16_bf16 v[22:25], v[184:185], v[54:55], v[22:25]
	s_waitcnt lgkmcnt(3)
	v_pk_mul_f32 v[32:33], v[32:33], v[198:199]
	v_mfma_f32_16x16x16_bf16 v[26:29], v[186:187], v[54:55], v[26:29]
	s_nop 0
	v_pk_mul_f32 v[30:31], v[30:31], v[196:197]
	s_nop 0
	v_add_u32_e32 v51, 0x3400, v49
	s_waitcnt lgkmcnt(2)
	v_mfma_f32_16x16x16_bf16 v[30:33], v[200:201], v[54:55], v[30:33]
	s_waitcnt lgkmcnt(1)
	v_pk_mul_f32 v[36:37], v[36:37], v[206:207]
	v_pk_mul_f32 v[34:35], v[34:35], v[204:205]
	s_nop 0
	s_waitcnt lgkmcnt(0)
	v_pk_mul_f32 v[40:41], v[40:41], v[210:211]
	v_mfma_f32_16x16x16_bf16 v[34:37], v[202:203], v[54:55], v[34:37]
	ds_read2_b64 v[66:69], v51 offset0:96 offset1:176
	v_pk_mul_f32 v[38:39], v[38:39], v[208:209]
	ds_read_b128 v[62:65], v17 offset:1472
	s_waitcnt lgkmcnt(0)
	v_pk_mul_f32 v[44:45], v[44:45], v[64:65]
	v_pk_mul_f32 v[42:43], v[42:43], v[62:63]
	v_mfma_f32_16x16x16_bf16 v[38:41], v[66:67], v[54:55], v[38:41]
	s_nop 0
	v_mfma_f32_16x16x16_bf16 v[42:45], v[68:69], v[54:55], v[42:45]
	s_and_b64 vcc, exec, s[38:39]
	s_cbranch_vccnz .LBB0_606
; __device__ __forceinline__ unsigned pk2(float lo, float hi) { f32x2_t v = {lo, hi}; bf16x2_t b = __builtin_convertvector(v, bf16x2_t); return __builtin_bit_cast(unsigned, b); }
; __device__ __forceinline__ f32x4 mfma16(bf16x4 a, bf16x4 b, f32x4 c) { return __builtin_amdgcn_mfma_f32_16x16x16bf16_1k(a, b, c, 0, 0, 0); }
; __device__ __forceinline__ bf16x4 pack4(f32x4 v) { u32x2 w; w.x = pk2(v[0], v[1]); w.y = pk2(v[2], v[3]); return __builtin_bit_cast(bf16x4, w); }
; __device__ __forceinline__ void hg_unit(const Ptrs& P, int l, int b, int hd, int ch, unsigned char* lds, int tid) {
;     ...
;     for (int j = 0; j < 8; ++j) {
;         if (j < nsub) {
;             const bf16x4 vf = *(const bf16x4*)(Vt + (j * 16 + lc) * 20 + 4 * g);
;             const bf16x4 atj = *(const bf16x4*)HG_ATT_SLOT(j);
;             f32x4 o = mfma16(vf, atj, (f32x4){0.f, 0.f, 0.f, 0.f});
;             if (j > 0) {
; #pragma unroll
;                 for (int kt = 0; kt < 8; ++kt) { const bf16x4 qf = *(const bf16x4*)(Qb + (16 * j + lc) * 136 + 16 * kt + 4 * g); o = mfma16(pack4(S[kt]), qf, o); } }
;             { u32x2 wv; wv.x = pk2(o[0], o[1]); wv.y = pk2(o[2], o[3]); *(u32x2*)(PJ + (row0 + 16 * j + lc) * PW + C_HI + hd * 128 + 16 * w + 4 * g) = wv; }
; #pragma unroll
;             for (int kt = 0; kt < 8; ++kt) { const f32x4 eb = *(const f32x4*)(EBE + j * 128 + 16 * kt + 4 * g);
;                 const bf16x4 kf = *(const bf16x4*)(Ket + (j * 128 + 16 * kt + lc) * 20 + 4 * g);
;                 S[kt] = mfma16(kf, vf, S[kt] * eb); }
.LBB0_615:
	v_or_b32_e32 v51, 48, v48
	v_mad_u32_u24 v54, v51, 40, v58
	ds_read_b64 v[54:55], v54
	ds_read_b64 v[150:151], v61 offset:13312
	v_mad_u32_u24 v51, v51, s26, v59
	ds_read2_b64 v[152:155], v51 offset1:4
	ds_read2_b64 v[156:159], v51 offset0:8 offset1:12
	ds_read2_b64 v[160:163], v51 offset0:16 offset1:20
	ds_read2_b64 v[164:167], v51 offset0:24 offset1:28
	ds_read_b128 v[168:171], v17 offset:1536
	s_mov_b32 s3, 0xc9000
	s_waitcnt lgkmcnt(5)
	v_mfma_f32_16x16x16_bf16 v[62:65], v[54:55], v[150:151], 0
	v_cvt_pk_bf16_f32 v56, v10, v11
	v_cvt_pk_bf16_f32 v57, v12, v13
	s_waitcnt lgkmcnt(4)
	s_nop 0
	v_mfma_f32_16x16x16_bf16 v[62:65], v[56:57], v[152:153], v[62:65]
	v_cvt_pk_bf16_f32 v56, v18, v19
	v_cvt_pk_bf16_f32 v57, v20, v21
	s_nop 1
	v_mfma_f32_16x16x16_bf16 v[62:65], v[56:57], v[154:155], v[62:65]
	s_nop 0
	v_cvt_pk_bf16_f32 v56, v22, v23
	v_cvt_pk_bf16_f32 v57, v24, v25
	s_waitcnt lgkmcnt(3)
	s_nop 0
	v_mfma_f32_16x16x16_bf16 v[62:65], v[56:57], v[156:157], v[62:65]
	v_cvt_pk_bf16_f32 v56, v26, v27
	v_cvt_pk_bf16_f32 v57, v28, v29
	s_nop 1
	v_mfma_f32_16x16x16_bf16 v[62:65], v[56:57], v[158:159], v[62:65]
	s_nop 0
	v_cvt_pk_bf16_f32 v56, v30, v31
	v_cvt_pk_bf16_f32 v57, v32, v33
	s_waitcnt lgkmcnt(2)
	s_nop 0
	v_mfma_f32_16x16x16_bf16 v[62:65], v[56:57], v[160:161], v[62:65]
	v_cvt_pk_bf16_f32 v56, v34, v35
	v_cvt_pk_bf16_f32 v57, v36, v37
	s_nop 1
	v_mfma_f32_16x16x16_bf16 v[62:65], v[56:57], v[162:163], v[62:65]
	s_nop 0
	v_cvt_pk_bf16_f32 v56, v38, v39
	v_cvt_pk_bf16_f32 v57, v40, v41
	v_mov_b32_e32 v51, v16
	s_waitcnt lgkmcnt(1)
	v_mfma_f32_16x16x16_bf16 v[62:65], v[56:57], v[164:165], v[62:65]
	v_cvt_pk_bf16_f32 v56, v42, v43
	v_cvt_pk_bf16_f32 v57, v44, v45
	s_nop 1
	v_mfma_f32_16x16x16_bf16 v[62:65], v[56:57], v[166:167], v[62:65]
	s_nop 7
	v_cvt_pk_bf16_f32 v56, v62, v63
	v_lshl_add_u64 v[62:63], v[52:53], 0, s[96:97]
	v_lshl_add_u64 v[62:63], v[46:47], 1, v[62:63]
	v_lshl_add_u64 v[62:63], v[62:63], 0, v[50:51]
	v_add_co_u32_e32 v62, vcc, s3, v62
	v_cvt_pk_bf16_f32 v57, v64, v65
	s_nop 0
	v_addc_co_u32_e32 v63, vcc, 0, v63, vcc
	global_store_dwordx2 v[62:63], v[56:57], off offset:2560
	s_nop 0
	v_add_u32_e32 v51, 0x3800, v49
	ds_read2_b64 v[172:175], v51 offset0:128 offset1:208
	ds_read_b128 v[176:179], v17 offset:1600
	ds_read_b128 v[180:183], v17 offset:1664
	v_add_u32_e32 v51, 0x4000, v49
	ds_read2_b64 v[184:187], v51 offset0:32 offset1:112
	ds_read_b128 v[188:191], v17 offset:1728
	ds_read_b128 v[196:199], v17 offset:1792
	s_waitcnt lgkmcnt(6)
	v_pk_mul_f32 v[12:13], v[12:13], v[170:171]
	v_pk_mul_f32 v[10:11], v[10:11], v[168:169]
	s_nop 0
	s_waitcnt lgkmcnt(4)
	v_pk_mul_f32 v[20:21], v[20:21], v[178:179]
	v_pk_mul_f32 v[18:19], v[18:19], v[176:177]
	s_nop 0
	v_mfma_f32_16x16x16_bf16 v[10:13], v[172:173], v[54:55], v[10:13]
	s_waitcnt lgkmcnt(3)
	v_pk_mul_f32 v[24:25], v[24:25], v[182:183]
	v_mfma_f32_16x16x16_bf16 v[18:21], v[174:175], v[54:55], v[18:21]
	s_nop 0
	v_pk_mul_f32 v[22:23], v[22:23], v[180:181]
	s_nop 0
	v_add_u32_e32 v51, 0x4400, v49
	ds_read2_b64 v[200:203], v51 offset0:64 offset1:144
	ds_read_b128 v[204:207], v17 offset:1856
	ds_read_b128 v[208:211], v17 offset:1920
	s_waitcnt lgkmcnt(5)
	v_mfma_f32_16x16x16_bf16 v[22:25], v[184:185], v[54:55], v[22:25]
	s_waitcnt lgkmcnt(4)
	v_pk_mul_f32 v[28:29], v[28:29], v[190:191]
	v_pk_mul_f32 v[26:27], v[26:27], v[188:189]
	s_nop 0
	s_waitcnt lgkmcnt(3)
	v_pk_mul_f32 v[32:33], v[32:33], v[198:199]
	v_mfma_f32_16x16x16_bf16 v[26:29], v[186:187], v[54:55], v[26:29]
	s_nop 0
	v_pk_mul_f32 v[30:31], v[30:31], v[196:197]
	s_nop 0
	v_add_u32_e32 v51, 0x4800, v49
	s_waitcnt lgkmcnt(2)
	v_mfma_f32_16x16x16_bf16 v[30:33], v[200:201], v[54:55], v[30:33]
	s_waitcnt lgkmcnt(1)
	v_pk_mul_f32 v[36:37], v[36:37], v[206:207]
	v_pk_mul_f32 v[34:35], v[34:35], v[204:205]
	s_nop 0
	s_waitcnt lgkmcnt(0)
	v_pk_mul_f32 v[40:41], v[40:41], v[210:211]
	v_mfma_f32_16x16x16_bf16 v[34:37], v[202:203], v[54:55], v[34:37]
	ds_read2_b64 v[66:69], v51 offset0:96 offset1:176
	v_pk_mul_f32 v[38:39], v[38:39], v[208:209]
	ds_read_b128 v[62:65], v17 offset:1984
	s_waitcnt lgkmcnt(0)
	v_pk_mul_f32 v[44:45], v[44:45], v[64:65]
	v_pk_mul_f32 v[42:43], v[42:43], v[62:63]
	v_mfma_f32_16x16x16_bf16 v[38:41], v[66:67], v[54:55], v[38:41]
	s_nop 0
	v_mfma_f32_16x16x16_bf16 v[42:45], v[68:69], v[54:55], v[42:45]
	s_and_b64 vcc, exec, s[38:39]
	s_cbranch_vccnz .LBB0_607
; __device__ __forceinline__ unsigned pk2(float lo, float hi) { f32x2_t v = {lo, hi}; bf16x2_t b = __builtin_convertvector(v, bf16x2_t); return __builtin_bit_cast(unsigned, b); }
; __device__ __forceinline__ f32x4 mfma16(bf16x4 a, bf16x4 b, f32x4 c) { return __builtin_amdgcn_mfma_f32_16x16x16bf16_1k(a, b, c, 0, 0, 0); }
; __device__ __forceinline__ bf16x4 pack4(f32x4 v) { u32x2 w; w.x = pk2(v[0], v[1]); w.y = pk2(v[2], v[3]); return __builtin_bit_cast(bf16x4, w); }
; __device__ __forceinline__ void hg_unit(const Ptrs& P, int l, int b, int hd, int ch, unsigned char* lds, int tid) {
;     ...
;     for (int j = 0; j < 8; ++j) {
;         if (j < nsub) {
;             const bf16x4 vf = *(const bf16x4*)(Vt + (j * 16 + lc) * 20 + 4 * g);
;             const bf16x4 atj = *(const bf16x4*)HG_ATT_SLOT(j);
;             f32x4 o = mfma16(vf, atj, (f32x4){0.f, 0.f, 0.f, 0.f});
;             if (j > 0) {
; #pragma unroll
;                 for (int kt = 0; kt < 8; ++kt) { const bf16x4 qf = *(const bf16x4*)(Qb + (16 * j + lc) * 136 + 16 * kt + 4 * g); o = mfma16(pack4(S[kt]), qf, o); } }
;             { u32x2 wv; wv.x = pk2(o[0], o[1]); wv.y = pk2(o[2], o[3]); *(u32x2*)(PJ + (row0 + 16 * j + lc) * PW + C_HI + hd * 128 + 16 * w + 4 * g) = wv; }
; #pragma unroll
;             for (int kt = 0; kt < 8; ++kt) { const f32x4 eb = *(const f32x4*)(EBE + j * 128 + 16 * kt + 4 * g);
;                 const bf16x4 kf = *(const bf16x4*)(Ket + (j * 128 + 16 * kt + lc) * 20 + 4 * g);
;                 S[kt] = mfma16(kf, vf, S[kt] * eb); }
.LBB0_616:
	v_or_b32_e32 v51, 64, v48
	v_mad_u32_u24 v54, v51, 40, v58
	ds_read_b64 v[54:55], v54
	ds_read_b64 v[150:151], v61 offset:17664
	v_mad_u32_u24 v51, v51, s26, v59
	ds_read2_b64 v[152:155], v51 offset1:4
	ds_read2_b64 v[156:159], v51 offset0:8 offset1:12
	ds_read2_b64 v[160:163], v51 offset0:16 offset1:20
	ds_read2_b64 v[164:167], v51 offset0:24 offset1:28
	ds_read_b128 v[168:171], v17 offset:2048
	s_mov_b32 s3, 0x10b000
	s_waitcnt lgkmcnt(5)
	v_mfma_f32_16x16x16_bf16 v[62:65], v[54:55], v[150:151], 0
	v_cvt_pk_bf16_f32 v56, v10, v11
	v_cvt_pk_bf16_f32 v57, v12, v13
	s_waitcnt lgkmcnt(4)
	s_nop 0
	v_mfma_f32_16x16x16_bf16 v[62:65], v[56:57], v[152:153], v[62:65]
	v_cvt_pk_bf16_f32 v56, v18, v19
	v_cvt_pk_bf16_f32 v57, v20, v21
	s_nop 1
	v_mfma_f32_16x16x16_bf16 v[62:65], v[56:57], v[154:155], v[62:65]
	s_nop 0
	v_cvt_pk_bf16_f32 v56, v22, v23
	v_cvt_pk_bf16_f32 v57, v24, v25
	s_waitcnt lgkmcnt(3)
	s_nop 0
	v_mfma_f32_16x16x16_bf16 v[62:65], v[56:57], v[156:157], v[62:65]
	v_cvt_pk_bf16_f32 v56, v26, v27
	v_cvt_pk_bf16_f32 v57, v28, v29
	s_nop 1
	v_mfma_f32_16x16x16_bf16 v[62:65], v[56:57], v[158:159], v[62:65]
	s_nop 0
	v_cvt_pk_bf16_f32 v56, v30, v31
	v_cvt_pk_bf16_f32 v57, v32, v33
	s_waitcnt lgkmcnt(2)
	s_nop 0
	v_mfma_f32_16x16x16_bf16 v[62:65], v[56:57], v[160:161], v[62:65]
	v_cvt_pk_bf16_f32 v56, v34, v35
	v_cvt_pk_bf16_f32 v57, v36, v37
	s_nop 1
	v_mfma_f32_16x16x16_bf16 v[62:65], v[56:57], v[162:163], v[62:65]
	s_nop 0
	v_cvt_pk_bf16_f32 v56, v38, v39
	v_cvt_pk_bf16_f32 v57, v40, v41
	v_mov_b32_e32 v51, v16
	s_waitcnt lgkmcnt(1)
	v_mfma_f32_16x16x16_bf16 v[62:65], v[56:57], v[164:165], v[62:65]
	v_cvt_pk_bf16_f32 v56, v42, v43
	v_cvt_pk_bf16_f32 v57, v44, v45
	s_nop 1
	v_mfma_f32_16x16x16_bf16 v[62:65], v[56:57], v[166:167], v[62:65]
	s_nop 7
	v_cvt_pk_bf16_f32 v56, v62, v63
	v_lshl_add_u64 v[62:63], v[52:53], 0, s[96:97]
	v_lshl_add_u64 v[62:63], v[46:47], 1, v[62:63]
	v_lshl_add_u64 v[62:63], v[62:63], 0, v[50:51]
	v_add_co_u32_e32 v62, vcc, s3, v62
	v_cvt_pk_bf16_f32 v57, v64, v65
	s_nop 0
	v_addc_co_u32_e32 v63, vcc, 0, v63, vcc
	global_store_dwordx2 v[62:63], v[56:57], off offset:2560
	s_nop 0
	v_add_u32_e32 v51, 0x5000, v49
	ds_read2_b64 v[172:175], v51 offset1:80
	ds_read_b128 v[176:179], v17 offset:2112
	ds_read_b128 v[180:183], v17 offset:2176
	ds_read2_b64 v[184:187], v51 offset0:160 offset1:240
	ds_read_b128 v[188:191], v17 offset:2240
	ds_read_b128 v[196:199], v17 offset:2304
	s_waitcnt lgkmcnt(6)
	v_pk_mul_f32 v[12:13], v[12:13], v[170:171]
	v_pk_mul_f32 v[10:11], v[10:11], v[168:169]
	s_nop 0
	s_waitcnt lgkmcnt(4)
	v_pk_mul_f32 v[20:21], v[20:21], v[178:179]
	v_pk_mul_f32 v[18:19], v[18:19], v[176:177]
	v_mfma_f32_16x16x16_bf16 v[10:13], v[172:173], v[54:55], v[10:13]
	s_nop 0
	v_mfma_f32_16x16x16_bf16 v[18:21], v[174:175], v[54:55], v[18:21]
	s_nop 0
	s_nop 0
	v_add_u32_e32 v51, 0x5800, v49
	ds_read2_b64 v[200:203], v51 offset0:64 offset1:144
	ds_read_b128 v[204:207], v17 offset:2368
	ds_read_b128 v[208:211], v17 offset:2432
	s_waitcnt lgkmcnt(6)
	v_pk_mul_f32 v[24:25], v[24:25], v[182:183]
	v_pk_mul_f32 v[22:23], v[22:23], v[180:181]
	s_nop 0
	s_waitcnt lgkmcnt(4)
	v_pk_mul_f32 v[28:29], v[28:29], v[190:191]
	v_pk_mul_f32 v[26:27], v[26:27], v[188:189]
	s_nop 0
	v_mfma_f32_16x16x16_bf16 v[22:25], v[184:185], v[54:55], v[22:25]
	s_waitcnt lgkmcnt(3)
	v_pk_mul_f32 v[32:33], v[32:33], v[198:199]
	v_mfma_f32_16x16x16_bf16 v[26:29], v[186:187], v[54:55], v[26:29]
	s_nop 0
	v_pk_mul_f32 v[30:31], v[30:31], v[196:197]
	s_nop 0
	v_add_u32_e32 v51, 0x5c00, v49
	s_waitcnt lgkmcnt(2)
	v_mfma_f32_16x16x16_bf16 v[30:33], v[200:201], v[54:55], v[30:33]
	s_waitcnt lgkmcnt(1)
	v_pk_mul_f32 v[36:37], v[36:37], v[206:207]
	v_pk_mul_f32 v[34:35], v[34:35], v[204:205]
	s_nop 0
	s_waitcnt lgkmcnt(0)
	v_pk_mul_f32 v[40:41], v[40:41], v[210:211]
	v_mfma_f32_16x16x16_bf16 v[34:37], v[202:203], v[54:55], v[34:37]
	ds_read2_b64 v[66:69], v51 offset0:96 offset1:176
	v_pk_mul_f32 v[38:39], v[38:39], v[208:209]
	ds_read_b128 v[62:65], v17 offset:2496
	s_waitcnt lgkmcnt(0)
	v_pk_mul_f32 v[44:45], v[44:45], v[64:65]
	v_pk_mul_f32 v[42:43], v[42:43], v[62:63]
	v_mfma_f32_16x16x16_bf16 v[38:41], v[66:67], v[54:55], v[38:41]
	s_nop 0
	v_mfma_f32_16x16x16_bf16 v[42:45], v[68:69], v[54:55], v[42:45]
	s_and_b64 vcc, exec, s[38:39]
	s_cbranch_vccnz .LBB0_608
; __device__ __forceinline__ unsigned pk2(float lo, float hi) { f32x2_t v = {lo, hi}; bf16x2_t b = __builtin_convertvector(v, bf16x2_t); return __builtin_bit_cast(unsigned, b); }
; __device__ __forceinline__ f32x4 mfma16(bf16x4 a, bf16x4 b, f32x4 c) { return __builtin_amdgcn_mfma_f32_16x16x16bf16_1k(a, b, c, 0, 0, 0); }
; __device__ __forceinline__ bf16x4 pack4(f32x4 v) { u32x2 w; w.x = pk2(v[0], v[1]); w.y = pk2(v[2], v[3]); return __builtin_bit_cast(bf16x4, w); }
; __device__ __forceinline__ void hg_unit(const Ptrs& P, int l, int b, int hd, int ch, unsigned char* lds, int tid) {
;     ...
;     for (int j = 0; j < 8; ++j) {
;         if (j < nsub) {
;             const bf16x4 vf = *(const bf16x4*)(Vt + (j * 16 + lc) * 20 + 4 * g);
;             const bf16x4 atj = *(const bf16x4*)HG_ATT_SLOT(j);
;             f32x4 o = mfma16(vf, atj, (f32x4){0.f, 0.f, 0.f, 0.f});
;             if (j > 0) {
; #pragma unroll
;                 for (int kt = 0; kt < 8; ++kt) { const bf16x4 qf = *(const bf16x4*)(Qb + (16 * j + lc) * 136 + 16 * kt + 4 * g); o = mfma16(pack4(S[kt]), qf, o); } }
;             { u32x2 wv; wv.x = pk2(o[0], o[1]); wv.y = pk2(o[2], o[3]); *(u32x2*)(PJ + (row0 + 16 * j + lc) * PW + C_HI + hd * 128 + 16 * w + 4 * g) = wv; }
; #pragma unroll
;             for (int kt = 0; kt < 8; ++kt) { const f32x4 eb = *(const f32x4*)(EBE + j * 128 + 16 * kt + 4 * g);
;                 const bf16x4 kf = *(const bf16x4*)(Ket + (j * 128 + 16 * kt + lc) * 20 + 4 * g);
;                 S[kt] = mfma16(kf, vf, S[kt] * eb); }
.LBB0_617:
	v_or_b32_e32 v51, 0x50, v48
	v_mad_u32_u24 v54, v51, 40, v58
	ds_read_b64 v[54:55], v54
	ds_read_b64 v[150:151], v61 offset:22016
	v_mad_u32_u24 v51, v51, s26, v59
	ds_read2_b64 v[152:155], v51 offset1:4
	ds_read2_b64 v[156:159], v51 offset0:8 offset1:12
	ds_read2_b64 v[160:163], v51 offset0:16 offset1:20
	ds_read2_b64 v[164:167], v51 offset0:24 offset1:28
	ds_read_b128 v[168:171], v17 offset:2560
	s_mov_b32 s3, 0x14d000
	s_waitcnt lgkmcnt(5)
	v_mfma_f32_16x16x16_bf16 v[62:65], v[54:55], v[150:151], 0
	v_cvt_pk_bf16_f32 v56, v10, v11
	v_cvt_pk_bf16_f32 v57, v12, v13
	s_waitcnt lgkmcnt(4)
	s_nop 0
	v_mfma_f32_16x16x16_bf16 v[62:65], v[56:57], v[152:153], v[62:65]
	v_cvt_pk_bf16_f32 v56, v18, v19
	v_cvt_pk_bf16_f32 v57, v20, v21
	s_nop 1
	v_mfma_f32_16x16x16_bf16 v[62:65], v[56:57], v[154:155], v[62:65]
	s_nop 0
	v_cvt_pk_bf16_f32 v56, v22, v23
	v_cvt_pk_bf16_f32 v57, v24, v25
	s_waitcnt lgkmcnt(3)
	s_nop 0
	v_mfma_f32_16x16x16_bf16 v[62:65], v[56:57], v[156:157], v[62:65]
	v_cvt_pk_bf16_f32 v56, v26, v27
	v_cvt_pk_bf16_f32 v57, v28, v29
	s_nop 1
	v_mfma_f32_16x16x16_bf16 v[62:65], v[56:57], v[158:159], v[62:65]
	s_nop 0
	v_cvt_pk_bf16_f32 v56, v30, v31
	v_cvt_pk_bf16_f32 v57, v32, v33
	s_waitcnt lgkmcnt(2)
	s_nop 0
	v_mfma_f32_16x16x16_bf16 v[62:65], v[56:57], v[160:161], v[62:65]
	v_cvt_pk_bf16_f32 v56, v34, v35
	v_cvt_pk_bf16_f32 v57, v36, v37
	s_nop 1
	v_mfma_f32_16x16x16_bf16 v[62:65], v[56:57], v[162:163], v[62:65]
	s_nop 0
	v_cvt_pk_bf16_f32 v56, v38, v39
	v_cvt_pk_bf16_f32 v57, v40, v41
	v_mov_b32_e32 v51, v16
	s_waitcnt lgkmcnt(1)
	v_mfma_f32_16x16x16_bf16 v[62:65], v[56:57], v[164:165], v[62:65]
	v_cvt_pk_bf16_f32 v56, v42, v43
	v_cvt_pk_bf16_f32 v57, v44, v45
	s_nop 1
	v_mfma_f32_16x16x16_bf16 v[62:65], v[56:57], v[166:167], v[62:65]
	s_nop 7
	v_cvt_pk_bf16_f32 v56, v62, v63
	v_lshl_add_u64 v[62:63], v[52:53], 0, s[96:97]
	v_lshl_add_u64 v[62:63], v[46:47], 1, v[62:63]
	v_lshl_add_u64 v[62:63], v[62:63], 0, v[50:51]
	v_add_co_u32_e32 v62, vcc, s3, v62
	v_cvt_pk_bf16_f32 v57, v64, v65
	s_nop 0
	v_addc_co_u32_e32 v63, vcc, 0, v63, vcc
	global_store_dwordx2 v[62:63], v[56:57], off offset:2560
	s_nop 0
	v_add_u32_e32 v51, 0x6000, v49
	ds_read2_b64 v[172:175], v51 offset0:128 offset1:208
	ds_read_b128 v[176:179], v17 offset:2624
	ds_read_b128 v[180:183], v17 offset:2688
	v_add_u32_e32 v51, 0x6800, v49
	ds_read2_b64 v[184:187], v51 offset0:32 offset1:112
	ds_read_b128 v[188:191], v17 offset:2752
	ds_read_b128 v[196:199], v17 offset:2816
	s_waitcnt lgkmcnt(6)
	v_pk_mul_f32 v[12:13], v[12:13], v[170:171]
	v_pk_mul_f32 v[10:11], v[10:11], v[168:169]
	s_nop 0
	s_waitcnt lgkmcnt(4)
	v_pk_mul_f32 v[20:21], v[20:21], v[178:179]
	v_pk_mul_f32 v[18:19], v[18:19], v[176:177]
	s_nop 0
	v_mfma_f32_16x16x16_bf16 v[10:13], v[172:173], v[54:55], v[10:13]
	s_waitcnt lgkmcnt(3)
	v_pk_mul_f32 v[24:25], v[24:25], v[182:183]
	v_mfma_f32_16x16x16_bf16 v[18:21], v[174:175], v[54:55], v[18:21]
	s_nop 0
	v_pk_mul_f32 v[22:23], v[22:23], v[180:181]
	s_nop 0
	v_add_u32_e32 v51, 0x6c00, v49
	ds_read2_b64 v[200:203], v51 offset0:64 offset1:144
	ds_read_b128 v[204:207], v17 offset:2880
	ds_read_b128 v[208:211], v17 offset:2944
	s_waitcnt lgkmcnt(5)
	v_mfma_f32_16x16x16_bf16 v[22:25], v[184:185], v[54:55], v[22:25]
	s_waitcnt lgkmcnt(4)
	v_pk_mul_f32 v[28:29], v[28:29], v[190:191]
	v_pk_mul_f32 v[26:27], v[26:27], v[188:189]
	s_nop 0
	s_waitcnt lgkmcnt(3)
	v_pk_mul_f32 v[32:33], v[32:33], v[198:199]
	v_mfma_f32_16x16x16_bf16 v[26:29], v[186:187], v[54:55], v[26:29]
	s_nop 0
	v_pk_mul_f32 v[30:31], v[30:31], v[196:197]
	s_nop 0
	v_add_u32_e32 v51, 0x7000, v49
	s_waitcnt lgkmcnt(2)
	v_mfma_f32_16x16x16_bf16 v[30:33], v[200:201], v[54:55], v[30:33]
	s_waitcnt lgkmcnt(1)
	v_pk_mul_f32 v[36:37], v[36:37], v[206:207]
	v_pk_mul_f32 v[34:35], v[34:35], v[204:205]
	s_nop 0
	s_waitcnt lgkmcnt(0)
	v_pk_mul_f32 v[40:41], v[40:41], v[210:211]
	v_mfma_f32_16x16x16_bf16 v[34:37], v[202:203], v[54:55], v[34:37]
	ds_read2_b64 v[66:69], v51 offset0:96 offset1:176
	v_pk_mul_f32 v[38:39], v[38:39], v[208:209]
	ds_read_b128 v[62:65], v17 offset:3008
	s_waitcnt lgkmcnt(0)
	v_pk_mul_f32 v[44:45], v[44:45], v[64:65]
	v_pk_mul_f32 v[42:43], v[42:43], v[62:63]
	v_mfma_f32_16x16x16_bf16 v[38:41], v[66:67], v[54:55], v[38:41]
	s_nop 0
	v_mfma_f32_16x16x16_bf16 v[42:45], v[68:69], v[54:55], v[42:45]
	s_and_b64 vcc, exec, s[38:39]
	s_cbranch_vccnz .LBB0_609
; __device__ __forceinline__ unsigned pk2(float lo, float hi) { f32x2_t v = {lo, hi}; bf16x2_t b = __builtin_convertvector(v, bf16x2_t); return __builtin_bit_cast(unsigned, b); }
; __device__ __forceinline__ f32x4 mfma16(bf16x4 a, bf16x4 b, f32x4 c) { return __builtin_amdgcn_mfma_f32_16x16x16bf16_1k(a, b, c, 0, 0, 0); }
; __device__ __forceinline__ bf16x4 pack4(f32x4 v) { u32x2 w; w.x = pk2(v[0], v[1]); w.y = pk2(v[2], v[3]); return __builtin_bit_cast(bf16x4, w); }
; __device__ __forceinline__ void hg_unit(const Ptrs& P, int l, int b, int hd, int ch, unsigned char* lds, int tid) {
;     ...
;     for (int j = 0; j < 8; ++j) {
;         if (j < nsub) {
;             const bf16x4 vf = *(const bf16x4*)(Vt + (j * 16 + lc) * 20 + 4 * g);
;             const bf16x4 atj = *(const bf16x4*)HG_ATT_SLOT(j);
;             f32x4 o = mfma16(vf, atj, (f32x4){0.f, 0.f, 0.f, 0.f});
;             if (j > 0) {
; #pragma unroll
;                 for (int kt = 0; kt < 8; ++kt) { const bf16x4 qf = *(const bf16x4*)(Qb + (16 * j + lc) * 136 + 16 * kt + 4 * g); o = mfma16(pack4(S[kt]), qf, o); } }
;             { u32x2 wv; wv.x = pk2(o[0], o[1]); wv.y = pk2(o[2], o[3]); *(u32x2*)(PJ + (row0 + 16 * j + lc) * PW + C_HI + hd * 128 + 16 * w + 4 * g) = wv; }
; #pragma unroll
;             for (int kt = 0; kt < 8; ++kt) { const f32x4 eb = *(const f32x4*)(EBE + j * 128 + 16 * kt + 4 * g);
;                 const bf16x4 kf = *(const bf16x4*)(Ket + (j * 128 + 16 * kt + lc) * 20 + 4 * g);
;                 S[kt] = mfma16(kf, vf, S[kt] * eb); }
.LBB0_618:
	v_or_b32_e32 v51, 0x60, v48
	v_mad_u32_u24 v54, v51, 40, v58
	ds_read_b64 v[54:55], v54
	ds_read_b64 v[150:151], v61 offset:26368
	v_mad_u32_u24 v51, v51, s26, v59
	ds_read2_b64 v[152:155], v51 offset1:4
	ds_read2_b64 v[156:159], v51 offset0:8 offset1:12
	ds_read2_b64 v[160:163], v51 offset0:16 offset1:20
	ds_read2_b64 v[164:167], v51 offset0:24 offset1:28
	ds_read_b128 v[168:171], v17 offset:3072
	s_mov_b32 s3, 0x18f000
	s_waitcnt lgkmcnt(5)
	v_mfma_f32_16x16x16_bf16 v[62:65], v[54:55], v[150:151], 0
	v_cvt_pk_bf16_f32 v56, v10, v11
	v_cvt_pk_bf16_f32 v57, v12, v13
	s_waitcnt lgkmcnt(4)
	s_nop 0
	v_mfma_f32_16x16x16_bf16 v[62:65], v[56:57], v[152:153], v[62:65]
	v_cvt_pk_bf16_f32 v56, v18, v19
	v_cvt_pk_bf16_f32 v57, v20, v21
	s_nop 1
	v_mfma_f32_16x16x16_bf16 v[62:65], v[56:57], v[154:155], v[62:65]
	s_nop 0
	v_cvt_pk_bf16_f32 v56, v22, v23
	v_cvt_pk_bf16_f32 v57, v24, v25
	s_waitcnt lgkmcnt(3)
	s_nop 0
	v_mfma_f32_16x16x16_bf16 v[62:65], v[56:57], v[156:157], v[62:65]
	v_cvt_pk_bf16_f32 v56, v26, v27
	v_cvt_pk_bf16_f32 v57, v28, v29
	s_nop 1
	v_mfma_f32_16x16x16_bf16 v[62:65], v[56:57], v[158:159], v[62:65]
	s_nop 0
	v_cvt_pk_bf16_f32 v56, v30, v31
	v_cvt_pk_bf16_f32 v57, v32, v33
	s_waitcnt lgkmcnt(2)
	s_nop 0
	v_mfma_f32_16x16x16_bf16 v[62:65], v[56:57], v[160:161], v[62:65]
	v_cvt_pk_bf16_f32 v56, v34, v35
	v_cvt_pk_bf16_f32 v57, v36, v37
	s_nop 1
	v_mfma_f32_16x16x16_bf16 v[62:65], v[56:57], v[162:163], v[62:65]
	s_nop 0
	v_cvt_pk_bf16_f32 v56, v38, v39
	v_cvt_pk_bf16_f32 v57, v40, v41
	v_mov_b32_e32 v51, v16
	s_waitcnt lgkmcnt(1)
	v_mfma_f32_16x16x16_bf16 v[62:65], v[56:57], v[164:165], v[62:65]
	v_cvt_pk_bf16_f32 v56, v42, v43
	v_cvt_pk_bf16_f32 v57, v44, v45
	s_nop 1
	v_mfma_f32_16x16x16_bf16 v[62:65], v[56:57], v[166:167], v[62:65]
	s_nop 7
	v_cvt_pk_bf16_f32 v56, v62, v63
	v_lshl_add_u64 v[62:63], v[52:53], 0, s[96:97]
	v_lshl_add_u64 v[62:63], v[46:47], 1, v[62:63]
	v_lshl_add_u64 v[62:63], v[62:63], 0, v[50:51]
	v_add_co_u32_e32 v62, vcc, s3, v62
	v_cvt_pk_bf16_f32 v57, v64, v65
	s_nop 0
	v_addc_co_u32_e32 v63, vcc, 0, v63, vcc
	global_store_dwordx2 v[62:63], v[56:57], off offset:2560
	s_nop 0
	v_add_u32_e32 v51, 0x7800, v49
	ds_read2_b64 v[172:175], v51 offset1:80
	ds_read_b128 v[176:179], v17 offset:3136
	ds_read_b128 v[180:183], v17 offset:3200
	ds_read2_b64 v[184:187], v51 offset0:160 offset1:240
	ds_read_b128 v[188:191], v17 offset:3264
	ds_read_b128 v[196:199], v17 offset:3328
	s_waitcnt lgkmcnt(6)
	v_pk_mul_f32 v[12:13], v[12:13], v[170:171]
	v_pk_mul_f32 v[10:11], v[10:11], v[168:169]
	s_nop 0
	s_waitcnt lgkmcnt(4)
	v_pk_mul_f32 v[20:21], v[20:21], v[178:179]
	v_pk_mul_f32 v[18:19], v[18:19], v[176:177]
	v_mfma_f32_16x16x16_bf16 v[10:13], v[172:173], v[54:55], v[10:13]
	s_nop 0
	v_mfma_f32_16x16x16_bf16 v[18:21], v[174:175], v[54:55], v[18:21]
	s_nop 0
	s_nop 0
	v_add_u32_e32 v51, 0x8000, v49
	ds_read2_b64 v[200:203], v51 offset0:64 offset1:144
	ds_read_b128 v[204:207], v17 offset:3392
	ds_read_b128 v[208:211], v17 offset:3456
	s_waitcnt lgkmcnt(6)
	v_pk_mul_f32 v[24:25], v[24:25], v[182:183]
	v_pk_mul_f32 v[22:23], v[22:23], v[180:181]
	s_nop 0
	s_waitcnt lgkmcnt(4)
	v_pk_mul_f32 v[28:29], v[28:29], v[190:191]
	v_pk_mul_f32 v[26:27], v[26:27], v[188:189]
	s_nop 0
	v_mfma_f32_16x16x16_bf16 v[22:25], v[184:185], v[54:55], v[22:25]
	s_waitcnt lgkmcnt(3)
	v_pk_mul_f32 v[32:33], v[32:33], v[198:199]
	v_mfma_f32_16x16x16_bf16 v[26:29], v[186:187], v[54:55], v[26:29]
	s_nop 0
	v_pk_mul_f32 v[30:31], v[30:31], v[196:197]
	s_nop 0
	v_add_u32_e32 v51, 0x8400, v49
	s_waitcnt lgkmcnt(2)
	v_mfma_f32_16x16x16_bf16 v[30:33], v[200:201], v[54:55], v[30:33]
	s_waitcnt lgkmcnt(1)
	v_pk_mul_f32 v[36:37], v[36:37], v[206:207]
	v_pk_mul_f32 v[34:35], v[34:35], v[204:205]
	s_nop 0
	s_waitcnt lgkmcnt(0)
	v_pk_mul_f32 v[40:41], v[40:41], v[210:211]
	v_mfma_f32_16x16x16_bf16 v[34:37], v[202:203], v[54:55], v[34:37]
	ds_read2_b64 v[66:69], v51 offset0:96 offset1:176
	v_pk_mul_f32 v[38:39], v[38:39], v[208:209]
	ds_read_b128 v[62:65], v17 offset:3520
	s_waitcnt lgkmcnt(0)
	v_pk_mul_f32 v[44:45], v[44:45], v[64:65]
	v_pk_mul_f32 v[42:43], v[42:43], v[62:63]
	v_mfma_f32_16x16x16_bf16 v[38:41], v[66:67], v[54:55], v[38:41]
	s_nop 0
	v_mfma_f32_16x16x16_bf16 v[42:45], v[68:69], v[54:55], v[42:45]
	s_and_b64 vcc, exec, s[38:39]
	s_cbranch_vccz .LBB0_610
	s_branch .LBB0_611
